# p3_tile latent-rms loop fully unrolled with 16 loads in flight; attention preamble reordered (LDS reads first)
# speedup vs baseline: 1.0162x; 1.0002x over previous
.LBB0_479:
	s_mov_b64 s[8:9], 0x0
	v_lshl_add_u64 v[204:205], v[2:3], 0, s[8:9]
	global_load_dwordx4 v[132:135], v[204:205], off offset:-1024 nt
	global_load_dwordx4 v[136:139], v[204:205], off nt
	global_load_dwordx4 v[140:143], v[204:205], off offset:-896 nt
	global_load_dwordx4 v[144:147], v[204:205], off offset:128 nt
	s_mov_b64 s[8:9], 0x100
	v_lshl_add_u64 v[204:205], v[2:3], 0, s[8:9]
	global_load_dwordx4 v[148:151], v[204:205], off offset:-1024 nt
	global_load_dwordx4 v[156:159], v[204:205], off nt
	global_load_dwordx4 v[160:163], v[204:205], off offset:-896 nt
	global_load_dwordx4 v[164:167], v[204:205], off offset:128 nt
	s_mov_b64 s[8:9], 0x200
	v_lshl_add_u64 v[204:205], v[2:3], 0, s[8:9]
	global_load_dwordx4 v[168:171], v[204:205], off offset:-1024 nt
	global_load_dwordx4 v[172:175], v[204:205], off nt
	global_load_dwordx4 v[176:179], v[204:205], off offset:-896 nt
	global_load_dwordx4 v[180:183], v[204:205], off offset:128 nt
	s_mov_b64 s[8:9], 0x300
	v_lshl_add_u64 v[204:205], v[2:3], 0, s[8:9]
	global_load_dwordx4 v[184:187], v[204:205], off offset:-1024 nt
	global_load_dwordx4 v[188:191], v[204:205], off nt
	global_load_dwordx4 v[192:195], v[204:205], off offset:-896 nt
	global_load_dwordx4 v[196:199], v[204:205], off offset:128 nt
	s_waitcnt vmcnt(12)
	v_mov_b32_e32 v4, v132
	v_mov_b32_e32 v5, v133
	v_mov_b32_e32 v6, v134
	v_mov_b32_e32 v7, v135
	v_mov_b32_e32 v12, v136
	v_mov_b32_e32 v13, v137
	v_mov_b32_e32 v14, v138
	v_mov_b32_e32 v15, v139
	v_mov_b32_e32 v16, v140
	v_mov_b32_e32 v17, v141
	v_mov_b32_e32 v18, v142
	v_mov_b32_e32 v19, v143
	v_mov_b32_e32 v20, v144
	v_mov_b32_e32 v21, v145
	v_mov_b32_e32 v22, v146
	v_mov_b32_e32 v23, v147
	v_lshlrev_b32_e32 v30, 16, v4
	v_lshlrev_b32_e32 v31, 16, v12
	v_and_b32_e32 v33, 0xffff0000, v12
	v_and_b32_e32 v32, 0xffff0000, v4
	v_pk_fma_f32 v[0:1], v[30:31], v[30:31], v[0:1]
	v_lshlrev_b32_e32 v34, 16, v5
	v_lshlrev_b32_e32 v35, 16, v13
	v_pk_fma_f32 v[0:1], v[32:33], v[32:33], v[0:1]
	v_and_b32_e32 v13, 0xffff0000, v13
	v_and_b32_e32 v12, 0xffff0000, v5
	v_pk_fma_f32 v[0:1], v[34:35], v[34:35], v[0:1]
	v_lshlrev_b32_e32 v4, 16, v6
	v_lshlrev_b32_e32 v5, 16, v14
	v_pk_fma_f32 v[0:1], v[12:13], v[12:13], v[0:1]
	v_and_b32_e32 v37, 0xffff0000, v14
	v_and_b32_e32 v36, 0xffff0000, v6
	v_pk_fma_f32 v[0:1], v[4:5], v[4:5], v[0:1]
	v_lshlrev_b32_e32 v38, 16, v7
	v_lshlrev_b32_e32 v39, 16, v15
	v_pk_fma_f32 v[0:1], v[36:37], v[36:37], v[0:1]
	v_and_b32_e32 v15, 0xffff0000, v15
	v_and_b32_e32 v14, 0xffff0000, v7
	v_pk_fma_f32 v[0:1], v[38:39], v[38:39], v[0:1]
	v_lshlrev_b32_e32 v6, 16, v16
	v_lshlrev_b32_e32 v7, 16, v20
	v_pk_fma_f32 v[0:1], v[14:15], v[14:15], v[0:1]
	v_and_b32_e32 v41, 0xffff0000, v20
	v_and_b32_e32 v40, 0xffff0000, v16
	v_pk_fma_f32 v[0:1], v[6:7], v[6:7], v[0:1]
	v_lshlrev_b32_e32 v42, 16, v17
	v_lshlrev_b32_e32 v43, 16, v21
	v_pk_fma_f32 v[0:1], v[40:41], v[40:41], v[0:1]
	v_and_b32_e32 v21, 0xffff0000, v21
	v_and_b32_e32 v20, 0xffff0000, v17
	v_pk_fma_f32 v[0:1], v[42:43], v[42:43], v[0:1]
	v_lshlrev_b32_e32 v16, 16, v18
	v_lshlrev_b32_e32 v17, 16, v22
	v_pk_fma_f32 v[0:1], v[20:21], v[20:21], v[0:1]
	v_and_b32_e32 v45, 0xffff0000, v22
	v_and_b32_e32 v44, 0xffff0000, v18
	v_pk_fma_f32 v[0:1], v[16:17], v[16:17], v[0:1]
	v_lshlrev_b32_e32 v46, 16, v19
	v_lshlrev_b32_e32 v47, 16, v23
	v_pk_fma_f32 v[0:1], v[44:45], v[44:45], v[0:1]
	v_and_b32_e32 v23, 0xffff0000, v23
	v_and_b32_e32 v22, 0xffff0000, v19
	v_pk_fma_f32 v[0:1], v[46:47], v[46:47], v[0:1]
	s_nop 0
	v_pk_fma_f32 v[0:1], v[22:23], v[22:23], v[0:1]
	s_waitcnt vmcnt(8)
	v_mov_b32_e32 v4, v148
	v_mov_b32_e32 v5, v149
	v_mov_b32_e32 v6, v150
	v_mov_b32_e32 v7, v151
	v_mov_b32_e32 v12, v156
	v_mov_b32_e32 v13, v157
	v_mov_b32_e32 v14, v158
	v_mov_b32_e32 v15, v159
	v_mov_b32_e32 v16, v160
	v_mov_b32_e32 v17, v161
	v_mov_b32_e32 v18, v162
	v_mov_b32_e32 v19, v163
	v_mov_b32_e32 v20, v164
	v_mov_b32_e32 v21, v165
	v_mov_b32_e32 v22, v166
	v_mov_b32_e32 v23, v167
	v_lshlrev_b32_e32 v30, 16, v4
	v_lshlrev_b32_e32 v31, 16, v12
	v_and_b32_e32 v33, 0xffff0000, v12
	v_and_b32_e32 v32, 0xffff0000, v4
	v_pk_fma_f32 v[0:1], v[30:31], v[30:31], v[0:1]
	v_lshlrev_b32_e32 v34, 16, v5
	v_lshlrev_b32_e32 v35, 16, v13
	v_pk_fma_f32 v[0:1], v[32:33], v[32:33], v[0:1]
	v_and_b32_e32 v13, 0xffff0000, v13
	v_and_b32_e32 v12, 0xffff0000, v5
	v_pk_fma_f32 v[0:1], v[34:35], v[34:35], v[0:1]
	v_lshlrev_b32_e32 v4, 16, v6
	v_lshlrev_b32_e32 v5, 16, v14
	v_pk_fma_f32 v[0:1], v[12:13], v[12:13], v[0:1]
	v_and_b32_e32 v37, 0xffff0000, v14
	v_and_b32_e32 v36, 0xffff0000, v6
	v_pk_fma_f32 v[0:1], v[4:5], v[4:5], v[0:1]
	v_lshlrev_b32_e32 v38, 16, v7
	v_lshlrev_b32_e32 v39, 16, v15
	v_pk_fma_f32 v[0:1], v[36:37], v[36:37], v[0:1]
	v_and_b32_e32 v15, 0xffff0000, v15
	v_and_b32_e32 v14, 0xffff0000, v7
	v_pk_fma_f32 v[0:1], v[38:39], v[38:39], v[0:1]
	v_lshlrev_b32_e32 v6, 16, v16
	v_lshlrev_b32_e32 v7, 16, v20
	v_pk_fma_f32 v[0:1], v[14:15], v[14:15], v[0:1]
	v_and_b32_e32 v41, 0xffff0000, v20
	v_and_b32_e32 v40, 0xffff0000, v16
	v_pk_fma_f32 v[0:1], v[6:7], v[6:7], v[0:1]
	v_lshlrev_b32_e32 v42, 16, v17
	v_lshlrev_b32_e32 v43, 16, v21
	v_pk_fma_f32 v[0:1], v[40:41], v[40:41], v[0:1]
	v_and_b32_e32 v21, 0xffff0000, v21
	v_and_b32_e32 v20, 0xffff0000, v17
	v_pk_fma_f32 v[0:1], v[42:43], v[42:43], v[0:1]
	v_lshlrev_b32_e32 v16, 16, v18
	v_lshlrev_b32_e32 v17, 16, v22
	v_pk_fma_f32 v[0:1], v[20:21], v[20:21], v[0:1]
	v_and_b32_e32 v45, 0xffff0000, v22
	v_and_b32_e32 v44, 0xffff0000, v18
	v_pk_fma_f32 v[0:1], v[16:17], v[16:17], v[0:1]
	v_lshlrev_b32_e32 v46, 16, v19
	v_lshlrev_b32_e32 v47, 16, v23
	v_pk_fma_f32 v[0:1], v[44:45], v[44:45], v[0:1]
	v_and_b32_e32 v23, 0xffff0000, v23
	v_and_b32_e32 v22, 0xffff0000, v19
	v_pk_fma_f32 v[0:1], v[46:47], v[46:47], v[0:1]
	s_nop 0
	v_pk_fma_f32 v[0:1], v[22:23], v[22:23], v[0:1]
	s_waitcnt vmcnt(4)
	v_mov_b32_e32 v4, v168
	v_mov_b32_e32 v5, v169
	v_mov_b32_e32 v6, v170
	v_mov_b32_e32 v7, v171
	v_mov_b32_e32 v12, v172
	v_mov_b32_e32 v13, v173
	v_mov_b32_e32 v14, v174
	v_mov_b32_e32 v15, v175
	v_mov_b32_e32 v16, v176
	v_mov_b32_e32 v17, v177
	v_mov_b32_e32 v18, v178
	v_mov_b32_e32 v19, v179
	v_mov_b32_e32 v20, v180
	v_mov_b32_e32 v21, v181
	v_mov_b32_e32 v22, v182
	v_mov_b32_e32 v23, v183
	v_lshlrev_b32_e32 v30, 16, v4
	v_lshlrev_b32_e32 v31, 16, v12
	v_and_b32_e32 v33, 0xffff0000, v12
	v_and_b32_e32 v32, 0xffff0000, v4
	v_pk_fma_f32 v[0:1], v[30:31], v[30:31], v[0:1]
	v_lshlrev_b32_e32 v34, 16, v5
	v_lshlrev_b32_e32 v35, 16, v13
	v_pk_fma_f32 v[0:1], v[32:33], v[32:33], v[0:1]
	v_and_b32_e32 v13, 0xffff0000, v13
	v_and_b32_e32 v12, 0xffff0000, v5
	v_pk_fma_f32 v[0:1], v[34:35], v[34:35], v[0:1]
	v_lshlrev_b32_e32 v4, 16, v6
	v_lshlrev_b32_e32 v5, 16, v14
	v_pk_fma_f32 v[0:1], v[12:13], v[12:13], v[0:1]
	v_and_b32_e32 v37, 0xffff0000, v14
	v_and_b32_e32 v36, 0xffff0000, v6
	v_pk_fma_f32 v[0:1], v[4:5], v[4:5], v[0:1]
	v_lshlrev_b32_e32 v38, 16, v7
	v_lshlrev_b32_e32 v39, 16, v15
	v_pk_fma_f32 v[0:1], v[36:37], v[36:37], v[0:1]
	v_and_b32_e32 v15, 0xffff0000, v15
	v_and_b32_e32 v14, 0xffff0000, v7
	v_pk_fma_f32 v[0:1], v[38:39], v[38:39], v[0:1]
	v_lshlrev_b32_e32 v6, 16, v16
	v_lshlrev_b32_e32 v7, 16, v20
	v_pk_fma_f32 v[0:1], v[14:15], v[14:15], v[0:1]
	v_and_b32_e32 v41, 0xffff0000, v20
	v_and_b32_e32 v40, 0xffff0000, v16
	v_pk_fma_f32 v[0:1], v[6:7], v[6:7], v[0:1]
	v_lshlrev_b32_e32 v42, 16, v17
	v_lshlrev_b32_e32 v43, 16, v21
	v_pk_fma_f32 v[0:1], v[40:41], v[40:41], v[0:1]
	v_and_b32_e32 v21, 0xffff0000, v21
	v_and_b32_e32 v20, 0xffff0000, v17
	v_pk_fma_f32 v[0:1], v[42:43], v[42:43], v[0:1]
	v_lshlrev_b32_e32 v16, 16, v18
	v_lshlrev_b32_e32 v17, 16, v22
	v_pk_fma_f32 v[0:1], v[20:21], v[20:21], v[0:1]
	v_and_b32_e32 v45, 0xffff0000, v22
	v_and_b32_e32 v44, 0xffff0000, v18
	v_pk_fma_f32 v[0:1], v[16:17], v[16:17], v[0:1]
	v_lshlrev_b32_e32 v46, 16, v19
	v_lshlrev_b32_e32 v47, 16, v23
	v_pk_fma_f32 v[0:1], v[44:45], v[44:45], v[0:1]
	v_and_b32_e32 v23, 0xffff0000, v23
	v_and_b32_e32 v22, 0xffff0000, v19
	v_pk_fma_f32 v[0:1], v[46:47], v[46:47], v[0:1]
	s_nop 0
	v_pk_fma_f32 v[0:1], v[22:23], v[22:23], v[0:1]
	s_waitcnt vmcnt(0)
	v_mov_b32_e32 v4, v184
	v_mov_b32_e32 v5, v185
	v_mov_b32_e32 v6, v186
	v_mov_b32_e32 v7, v187
	v_mov_b32_e32 v12, v188
	v_mov_b32_e32 v13, v189
	v_mov_b32_e32 v14, v190
	v_mov_b32_e32 v15, v191
	v_mov_b32_e32 v16, v192
	v_mov_b32_e32 v17, v193
	v_mov_b32_e32 v18, v194
	v_mov_b32_e32 v19, v195
	v_mov_b32_e32 v20, v196
	v_mov_b32_e32 v21, v197
	v_mov_b32_e32 v22, v198
	v_mov_b32_e32 v23, v199
	v_lshlrev_b32_e32 v30, 16, v4
	v_lshlrev_b32_e32 v31, 16, v12
	v_and_b32_e32 v33, 0xffff0000, v12
	v_and_b32_e32 v32, 0xffff0000, v4
	v_pk_fma_f32 v[0:1], v[30:31], v[30:31], v[0:1]
	v_lshlrev_b32_e32 v34, 16, v5
	v_lshlrev_b32_e32 v35, 16, v13
	v_pk_fma_f32 v[0:1], v[32:33], v[32:33], v[0:1]
	v_and_b32_e32 v13, 0xffff0000, v13
	v_and_b32_e32 v12, 0xffff0000, v5
	v_pk_fma_f32 v[0:1], v[34:35], v[34:35], v[0:1]
	v_lshlrev_b32_e32 v4, 16, v6
	v_lshlrev_b32_e32 v5, 16, v14
	v_pk_fma_f32 v[0:1], v[12:13], v[12:13], v[0:1]
	v_and_b32_e32 v37, 0xffff0000, v14
	v_and_b32_e32 v36, 0xffff0000, v6
	v_pk_fma_f32 v[0:1], v[4:5], v[4:5], v[0:1]
	v_lshlrev_b32_e32 v38, 16, v7
	v_lshlrev_b32_e32 v39, 16, v15
	v_pk_fma_f32 v[0:1], v[36:37], v[36:37], v[0:1]
	v_and_b32_e32 v15, 0xffff0000, v15
	v_and_b32_e32 v14, 0xffff0000, v7
	v_pk_fma_f32 v[0:1], v[38:39], v[38:39], v[0:1]
	v_lshlrev_b32_e32 v6, 16, v16
	v_lshlrev_b32_e32 v7, 16, v20
	v_pk_fma_f32 v[0:1], v[14:15], v[14:15], v[0:1]
	v_and_b32_e32 v41, 0xffff0000, v20
	v_and_b32_e32 v40, 0xffff0000, v16
	v_pk_fma_f32 v[0:1], v[6:7], v[6:7], v[0:1]
	v_lshlrev_b32_e32 v42, 16, v17
	v_lshlrev_b32_e32 v43, 16, v21
	v_pk_fma_f32 v[0:1], v[40:41], v[40:41], v[0:1]
	v_and_b32_e32 v21, 0xffff0000, v21
	v_and_b32_e32 v20, 0xffff0000, v17
	v_pk_fma_f32 v[0:1], v[42:43], v[42:43], v[0:1]
	v_lshlrev_b32_e32 v16, 16, v18
	v_lshlrev_b32_e32 v17, 16, v22
	v_pk_fma_f32 v[0:1], v[20:21], v[20:21], v[0:1]
	v_and_b32_e32 v45, 0xffff0000, v22
	v_and_b32_e32 v44, 0xffff0000, v18
	v_pk_fma_f32 v[0:1], v[16:17], v[16:17], v[0:1]
	v_lshlrev_b32_e32 v46, 16, v19
	v_lshlrev_b32_e32 v47, 16, v23
	v_pk_fma_f32 v[0:1], v[44:45], v[44:45], v[0:1]
	v_and_b32_e32 v23, 0xffff0000, v23
	v_and_b32_e32 v22, 0xffff0000, v19
	v_pk_fma_f32 v[0:1], v[46:47], v[46:47], v[0:1]
	s_nop 0
	v_pk_fma_f32 v[0:1], v[22:23], v[22:23], v[0:1]
	v_readlane_b32 s8, v246, 36
	s_lshl_b32 s15, s20, 6
	v_readlane_b32 s9, v246, 37
	v_and_b32_e32 v29, 7, v27
	v_add_u32_e32 v2, s15, v28
	v_mov_b64_e32 v[4:5], s[8:9]
	v_mad_i64_i32 v[4:5], s[8:9], v2, s11, v[4:5]
	v_lshlrev_b32_e32 v24, 4, v29
	v_lshl_add_u64 v[4:5], v[4:5], 0, v[24:25]
	v_add_co_u32_e32 v4, vcc, 0x2000, v4
	v_and_b32_e32 v9, 64, v54
	s_nop 0
	v_addc_co_u32_e32 v5, vcc, 0, v5, vcc
	global_load_dwordx4 v[4:7], v[4:5], off offset:2048 nt
	v_xor_b32_e32 v3, 1, v54
	v_add_u32_e32 v9, 64, v9
	v_cmp_lt_i32_e32 vcc, v3, v9
	v_xor_b32_e32 v12, 2, v54
	s_waitcnt vmcnt(0)
	v_lshlrev_b32_e32 v30, 16, v4
	v_cndmask_b32_e32 v3, v54, v3, vcc
	v_lshlrev_b32_e32 v57, 2, v3
	ds_bpermute_b32 v3, v57, v0
	v_cmp_lt_i32_e32 vcc, v12, v9
	v_and_b32_e32 v31, 0xffff0000, v4
	v_lshlrev_b32_e32 v32, 16, v5
	v_cndmask_b32_e32 v12, v54, v12, vcc
	v_lshlrev_b32_e32 v58, 2, v12
	s_waitcnt lgkmcnt(0)
	v_add_f32_e32 v0, v0, v3
	ds_bpermute_b32 v3, v58, v0
	v_and_b32_e32 v33, 0xffff0000, v5
	v_pk_mul_f32 v[4:5], v[30:31], v[30:31]
	v_lshlrev_b32_e32 v34, 16, v6
	v_and_b32_e32 v35, 0xffff0000, v6
	s_waitcnt lgkmcnt(0)
	v_add_f32_e32 v0, v0, v3
	v_lshlrev_b32_e32 v36, 16, v7
	v_and_b32_e32 v37, 0xffff0000, v7
	v_pk_mul_f32 v[6:7], v[32:33], v[32:33]
	v_add_f32_e32 v3, v4, v5
	v_add_f32_e32 v3, v6, v3
	v_pk_mul_f32 v[12:13], v[34:35], v[34:35]
	v_add_f32_e32 v3, v7, v3
	v_add_f32_e32 v3, v12, v3
	v_pk_mul_f32 v[14:15], v[36:37], v[36:37]
	v_add_f32_e32 v3, v13, v3
	v_add_f32_e32 v3, v14, v3
	v_add_f32_e32 v3, v15, v3
	ds_bpermute_b32 v16, v57, v1
	ds_bpermute_b32 v5, v57, v3
	v_xor_b32_e32 v4, 4, v54
	v_cmp_lt_i32_e32 vcc, v4, v9
	s_waitcnt lgkmcnt(1)
	v_add_f32_e32 v6, v1, v16
	s_waitcnt lgkmcnt(0)
	v_add_f32_e32 v3, v3, v5
	ds_bpermute_b32 v7, v58, v6
	ds_bpermute_b32 v5, v58, v3
	v_cndmask_b32_e32 v4, v54, v4, vcc
	v_lshlrev_b32_e32 v59, 2, v4
	ds_bpermute_b32 v1, v59, v0
	s_waitcnt lgkmcnt(2)
	v_add_f32_e32 v9, v6, v7
	s_waitcnt lgkmcnt(1)
	v_add_f32_e32 v13, v3, v5
	ds_bpermute_b32 v12, v59, v9
	ds_bpermute_b32 v14, v59, v13
	v_ashrrev_i32_e32 v3, 31, v2
	v_cmp_eq_u32_e32 vcc, 0, v29
	s_and_saveexec_b64 s[8:9], vcc
	s_cbranch_execz .LBB0_482
	s_waitcnt lgkmcnt(2)
	v_add_f32_e32 v0, v0, v1
	v_fmamk_f32 v0, v0, 0x3b000000, v55
	v_mul_f32_e32 v1, 0x4b800000, v0
	v_cmp_gt_f32_e32 vcc, s16, v0
	s_nop 1
	v_cndmask_b32_e32 v0, v0, v1, vcc
	v_rsq_f32_e32 v4, v0
	v_lshl_add_u64 v[0:1], v[2:3], 2, s[92:93]
	v_mul_f32_e32 v5, 0x45800000, v4
	v_cndmask_b32_e32 v4, v4, v5, vcc
	global_store_dword v[0:1], v4, off

.LBB0_630:
	v_rsq_f32_e32 v0, v110
	v_and_b32_e32 v111, 0xffff0000, v18
	s_lshl_b32 s10, s1, 2
	s_ashr_i32 s1, s9, 7
	v_mul_f32_e32 v110, 0x45800000, v0
	v_cndmask_b32_e32 v0, v0, v110, vcc
	v_mul_f32_e32 v0, v235, v0
	v_mul_f32_e32 v0, 0x3dd53b94, v0
	v_lshlrev_b32_e32 v110, 16, v18
	v_lshlrev_b32_e32 v18, 16, v19
	v_and_b32_e32 v19, 0xffff0000, v19
	v_pk_mul_f32 v[18:19], v[0:1], v[18:19] op_sel_hi:[0,1]
	v_pk_mul_f32 v[110:111], v[0:1], v[110:111] op_sel_hi:[0,1]
	v_pk_mul_f32 v[18:19], v[134:135], v[18:19]
	v_pk_mul_f32 v[110:111], v[132:133], v[110:111]
	v_cvt_pk_bf16_f32 v133, v18, v19
	v_lshlrev_b32_e32 v18, 16, v20
	v_and_b32_e32 v19, 0xffff0000, v20
	v_pk_mul_f32 v[18:19], v[0:1], v[18:19] op_sel_hi:[0,1]
	v_pk_mul_f32 v[18:19], v[196:197], v[18:19]
	v_lshlrev_b32_e32 v20, 16, v49
	v_cvt_pk_bf16_f32 v134, v18, v19
	v_lshlrev_b32_e32 v18, 16, v21
	v_and_b32_e32 v19, 0xffff0000, v21
	v_pk_mul_f32 v[18:19], v[0:1], v[18:19] op_sel_hi:[0,1]
	v_pk_mul_f32 v[18:19], v[198:199], v[18:19]
	v_and_b32_e32 v21, 0xffff0000, v49
	v_cvt_pk_bf16_f32 v135, v18, v19
	v_lshlrev_b32_e32 v18, 16, v6
	v_and_b32_e32 v19, 0xffff0000, v6
	v_lshlrev_b32_e32 v6, 16, v7
	v_and_b32_e32 v7, 0xffff0000, v7
	v_pk_mul_f32 v[6:7], v[0:1], v[6:7] op_sel_hi:[0,1]
	v_pk_mul_f32 v[18:19], v[0:1], v[18:19] op_sel_hi:[0,1]
	v_pk_mul_f32 v[6:7], v[138:139], v[6:7]
	v_pk_mul_f32 v[18:19], v[136:137], v[18:19]
	v_cvt_pk_bf16_f32 v137, v6, v7
	v_lshlrev_b32_e32 v6, 16, v8
	v_and_b32_e32 v7, 0xffff0000, v8
	v_pk_mul_f32 v[6:7], v[0:1], v[6:7] op_sel_hi:[0,1]
	v_pk_mul_f32 v[6:7], v[192:193], v[6:7]
	v_lshlrev_b32_e32 v8, 16, v46
	v_cvt_pk_bf16_f32 v138, v6, v7
	v_lshlrev_b32_e32 v6, 16, v9
	v_and_b32_e32 v7, 0xffff0000, v9
	v_pk_mul_f32 v[6:7], v[0:1], v[6:7] op_sel_hi:[0,1]
	v_pk_mul_f32 v[6:7], v[194:195], v[6:7]
	v_and_b32_e32 v9, 0xffff0000, v46
	v_cvt_pk_bf16_f32 v139, v6, v7
	v_lshlrev_b32_e32 v6, 16, v14
	v_and_b32_e32 v7, 0xffff0000, v14
	v_pk_mul_f32 v[6:7], v[0:1], v[6:7] op_sel_hi:[0,1]
	v_pk_mul_f32 v[6:7], v[140:141], v[6:7]
	v_pk_mul_f32 v[8:9], v[0:1], v[8:9] op_sel_hi:[0,1]
	v_cvt_pk_bf16_f32 v140, v6, v7
	v_lshlrev_b32_e32 v6, 16, v15
	v_and_b32_e32 v7, 0xffff0000, v15
	v_pk_mul_f32 v[6:7], v[0:1], v[6:7] op_sel_hi:[0,1]
	v_pk_mul_f32 v[6:7], v[142:143], v[6:7]
	v_pk_mul_f32 v[8:9], v[148:149], v[8:9]
	v_cvt_pk_bf16_f32 v141, v6, v7
	v_lshlrev_b32_e32 v6, 16, v16
	v_and_b32_e32 v7, 0xffff0000, v16
	v_pk_mul_f32 v[6:7], v[0:1], v[6:7] op_sel_hi:[0,1]
	v_pk_mul_f32 v[6:7], v[188:189], v[6:7]
	v_lshlrev_b32_e32 v16, 16, v48
	v_cvt_pk_bf16_f32 v142, v6, v7
	v_lshlrev_b32_e32 v6, 16, v17
	v_and_b32_e32 v7, 0xffff0000, v17
	v_pk_mul_f32 v[6:7], v[0:1], v[6:7] op_sel_hi:[0,1]
	v_pk_mul_f32 v[6:7], v[190:191], v[6:7]
	v_and_b32_e32 v17, 0xffff0000, v48
	v_cvt_pk_bf16_f32 v143, v6, v7
	v_lshlrev_b32_e32 v6, 16, v10
	v_and_b32_e32 v7, 0xffff0000, v10
	v_pk_mul_f32 v[6:7], v[0:1], v[6:7] op_sel_hi:[0,1]
	v_pk_mul_f32 v[6:7], v[144:145], v[6:7]
	v_pk_mul_f32 v[16:17], v[0:1], v[16:17] op_sel_hi:[0,1]
	v_cvt_pk_bf16_f32 v144, v6, v7
	v_lshlrev_b32_e32 v6, 16, v11
	v_and_b32_e32 v7, 0xffff0000, v11
	v_pk_mul_f32 v[6:7], v[0:1], v[6:7] op_sel_hi:[0,1]
	v_pk_mul_f32 v[6:7], v[146:147], v[6:7]
	v_pk_mul_f32 v[10:11], v[102:103], v[8:9]
	v_cvt_pk_bf16_f32 v145, v6, v7
	v_lshlrev_b32_e32 v6, 16, v12
	v_and_b32_e32 v7, 0xffff0000, v12
	v_pk_mul_f32 v[6:7], v[0:1], v[6:7] op_sel_hi:[0,1]
	v_pk_mul_f32 v[6:7], v[184:185], v[6:7]
	v_lshlrev_b32_e32 v12, 16, v47
	v_cvt_pk_bf16_f32 v146, v6, v7
	v_lshlrev_b32_e32 v6, 16, v13
	v_and_b32_e32 v7, 0xffff0000, v13
	v_pk_mul_f32 v[6:7], v[0:1], v[6:7] op_sel_hi:[0,1]
	v_pk_mul_f32 v[6:7], v[186:187], v[6:7]
	v_and_b32_e32 v13, 0xffff0000, v47
	v_cvt_pk_bf16_f32 v147, v6, v7
	v_lshlrev_b32_e32 v6, 16, v30
	v_and_b32_e32 v7, 0xffff0000, v30
	v_pk_mul_f32 v[6:7], v[0:1], v[6:7] op_sel_hi:[0,1]
	v_pk_mul_f32 v[6:7], v[152:153], v[6:7]
	v_pk_mul_f32 v[12:13], v[0:1], v[12:13] op_sel_hi:[0,1]
	v_cvt_pk_bf16_f32 v152, v6, v7
	v_lshlrev_b32_e32 v6, 16, v31
	v_and_b32_e32 v7, 0xffff0000, v31
	v_pk_mul_f32 v[6:7], v[0:1], v[6:7] op_sel_hi:[0,1]
	v_pk_mul_f32 v[6:7], v[154:155], v[6:7]
	v_pk_mul_f32 v[12:13], v[150:151], v[12:13]
	v_cvt_pk_bf16_f32 v153, v6, v7
	v_lshlrev_b32_e32 v6, 16, v32
	v_and_b32_e32 v7, 0xffff0000, v32
	v_pk_mul_f32 v[6:7], v[0:1], v[6:7] op_sel_hi:[0,1]
	v_pk_mul_f32 v[6:7], v[180:181], v[6:7]
	v_pk_mul_f32 v[14:15], v[104:105], v[12:13]
	v_cvt_pk_bf16_f32 v154, v6, v7
	v_lshlrev_b32_e32 v6, 16, v33
	v_and_b32_e32 v7, 0xffff0000, v33
	v_pk_mul_f32 v[6:7], v[0:1], v[6:7] op_sel_hi:[0,1]
	v_pk_mul_f32 v[6:7], v[182:183], v[6:7]
	v_pk_mul_f32 v[16:17], v[94:95], v[16:17]
	v_cvt_pk_bf16_f32 v155, v6, v7
	v_lshlrev_b32_e32 v6, 16, v22
	v_and_b32_e32 v7, 0xffff0000, v22
	v_pk_mul_f32 v[6:7], v[0:1], v[6:7] op_sel_hi:[0,1]
	v_pk_mul_f32 v[6:7], v[164:165], v[6:7]
	v_cvt_pk_bf16_f32 v136, v18, v19
	v_cvt_pk_bf16_f32 v164, v6, v7
	v_lshlrev_b32_e32 v6, 16, v23
	v_and_b32_e32 v7, 0xffff0000, v23
	v_pk_mul_f32 v[6:7], v[0:1], v[6:7] op_sel_hi:[0,1]
	v_pk_mul_f32 v[6:7], v[166:167], v[6:7]
	v_pk_mul_f32 v[18:19], v[86:87], v[16:17]
	v_cvt_pk_bf16_f32 v165, v6, v7
	v_lshlrev_b32_e32 v6, 16, v24
	v_and_b32_e32 v7, 0xffff0000, v24
	v_pk_mul_f32 v[6:7], v[0:1], v[6:7] op_sel_hi:[0,1]
	v_pk_mul_f32 v[6:7], v[176:177], v[6:7]
	v_pk_mul_f32 v[20:21], v[0:1], v[20:21] op_sel_hi:[0,1]
	v_cvt_pk_bf16_f32 v166, v6, v7
	v_lshlrev_b32_e32 v6, 16, v25
	v_and_b32_e32 v7, 0xffff0000, v25
	v_pk_mul_f32 v[6:7], v[0:1], v[6:7] op_sel_hi:[0,1]
	v_pk_mul_f32 v[6:7], v[178:179], v[6:7]
	v_pk_mul_f32 v[20:21], v[96:97], v[20:21]
	v_cvt_pk_bf16_f32 v167, v6, v7
	v_lshlrev_b32_e32 v6, 16, v42
	v_and_b32_e32 v7, 0xffff0000, v42
	v_pk_mul_f32 v[6:7], v[0:1], v[6:7] op_sel_hi:[0,1]
	v_pk_mul_f32 v[6:7], v[172:173], v[6:7]
	v_pk_mul_f32 v[22:23], v[88:89], v[20:21]
	v_cvt_pk_bf16_f32 v172, v6, v7
	v_lshlrev_b32_e32 v6, 16, v43
	v_and_b32_e32 v7, 0xffff0000, v43
	v_pk_mul_f32 v[6:7], v[0:1], v[6:7] op_sel_hi:[0,1]
	v_pk_mul_f32 v[6:7], v[174:175], v[6:7]
	s_xor_b64 s[2:3], s[2:3], -1
	v_cvt_pk_bf16_f32 v173, v6, v7
	v_lshlrev_b32_e32 v6, 16, v44
	v_and_b32_e32 v7, 0xffff0000, v44
	v_pk_mul_f32 v[6:7], v[0:1], v[6:7] op_sel_hi:[0,1]
	v_pk_mul_f32 v[6:7], v[168:169], v[6:7]
	v_lshlrev_b32_e32 v201, 3, v237
	v_cvt_pk_bf16_f32 v174, v6, v7
	v_lshlrev_b32_e32 v6, 16, v45
	v_and_b32_e32 v7, 0xffff0000, v45
	v_pk_mul_f32 v[6:7], v[0:1], v[6:7] op_sel_hi:[0,1]
	v_pk_mul_f32 v[6:7], v[170:171], v[6:7]
	v_cvt_pk_bf16_f32 v132, v110, v111
	v_cvt_pk_bf16_f32 v175, v6, v7
	v_lshlrev_b32_e32 v6, 16, v38
	v_and_b32_e32 v7, 0xffff0000, v38
	v_pk_mul_f32 v[6:7], v[0:1], v[6:7] op_sel_hi:[0,1]
	v_pk_mul_f32 v[6:7], v[160:161], v[6:7]
	s_add_i32 s1, s1, s10
	v_cvt_pk_bf16_f32 v160, v6, v7
	v_lshlrev_b32_e32 v6, 16, v39
	v_and_b32_e32 v7, 0xffff0000, v39
	v_pk_mul_f32 v[6:7], v[0:1], v[6:7] op_sel_hi:[0,1]
	v_pk_mul_f32 v[6:7], v[162:163], v[6:7]
	s_mov_b32 s6, 1
	v_cvt_pk_bf16_f32 v161, v6, v7
	v_lshlrev_b32_e32 v6, 16, v40
	v_and_b32_e32 v7, 0xffff0000, v40
	v_pk_mul_f32 v[6:7], v[0:1], v[6:7] op_sel_hi:[0,1]
	v_pk_mul_f32 v[6:7], v[156:157], v[6:7]
	v_mul_u32_u24_e32 v181, 0x90, v228
	v_cvt_pk_bf16_f32 v162, v6, v7
	v_lshlrev_b32_e32 v6, 16, v41
	v_and_b32_e32 v7, 0xffff0000, v41
	v_pk_mul_f32 v[6:7], v[0:1], v[6:7] op_sel_hi:[0,1]
	v_pk_mul_f32 v[6:7], v[158:159], v[6:7]
	s_or_b32 s7, s10, 2
	v_cvt_pk_bf16_f32 v163, v6, v7
	v_lshlrev_b32_e32 v6, 16, v26
	v_and_b32_e32 v7, 0xffff0000, v26
	v_pk_mul_f32 v[6:7], v[0:1], v[6:7] op_sel_hi:[0,1]
	v_pk_mul_f32 v[6:7], v[106:107], v[6:7]
	s_add_i32 s9, s10, 4
	v_pk_fma_f32 v[10:11], v[98:99], v[6:7], v[10:11] neg_lo:[0,0,1] neg_hi:[0,0,1]
	v_pk_mul_f32 v[6:7], v[102:103], v[6:7]
	v_cvt_pk_bf16_f32 v148, v10, v11
	v_pk_fma_f32 v[6:7], v[98:99], v[8:9], v[6:7]
	v_lshlrev_b32_e32 v8, 16, v27
	v_and_b32_e32 v9, 0xffff0000, v27
	v_pk_mul_f32 v[8:9], v[0:1], v[8:9] op_sel_hi:[0,1]
	v_pk_mul_f32 v[8:9], v[108:109], v[8:9]
	v_cvt_pk_bf16_f32 v156, v6, v7
	v_pk_fma_f32 v[14:15], v[100:101], v[8:9], v[14:15] neg_lo:[0,0,1] neg_hi:[0,0,1]
	v_pk_mul_f32 v[8:9], v[104:105], v[8:9]
	v_lshlrev_b32_e32 v6, 16, v2
	v_pk_fma_f32 v[8:9], v[100:101], v[12:13], v[8:9]
	v_and_b32_e32 v7, 0xffff0000, v2
	v_cvt_pk_bf16_f32 v157, v8, v9
	v_lshlrev_b32_e32 v8, 16, v34
	v_and_b32_e32 v9, 0xffff0000, v34
	v_pk_mul_f32 v[8:9], v[0:1], v[8:9] op_sel_hi:[0,1]
	v_pk_mul_f32 v[6:7], v[0:1], v[6:7] op_sel_hi:[0,1]
	v_pk_mul_f32 v[8:9], v[78:79], v[8:9]
	v_lshlrev_b32_e32 v12, 16, v28
	v_and_b32_e32 v13, 0xffff0000, v28
	v_pk_mul_f32 v[6:7], v[74:75], v[6:7]
	v_pk_mul_f32 v[10:11], v[70:71], v[8:9]
	v_pk_mul_f32 v[12:13], v[0:1], v[12:13] op_sel_hi:[0,1]
	v_pk_fma_f32 v[10:11], v[66:67], v[6:7], v[10:11] neg_lo:[0,0,1] neg_hi:[0,0,1]
	v_pk_mul_f32 v[6:7], v[70:71], v[6:7]
	v_pk_mul_f32 v[12:13], v[90:91], v[12:13]
	v_pk_fma_f32 v[6:7], v[66:67], v[8:9], v[6:7]
	v_lshlrev_b32_e32 v8, 16, v35
	v_and_b32_e32 v9, 0xffff0000, v35
	v_pk_fma_f32 v[18:19], v[82:83], v[12:13], v[18:19] neg_lo:[0,0,1] neg_hi:[0,0,1]
	v_pk_mul_f32 v[12:13], v[86:87], v[12:13]
	v_lshlrev_b32_e32 v2, 16, v3
	v_and_b32_e32 v3, 0xffff0000, v3
	v_pk_mul_f32 v[8:9], v[0:1], v[8:9] op_sel_hi:[0,1]
	v_pk_fma_f32 v[12:13], v[82:83], v[16:17], v[12:13]
	v_lshlrev_b32_e32 v16, 16, v29
	v_and_b32_e32 v17, 0xffff0000, v29
	v_pk_mul_f32 v[2:3], v[0:1], v[2:3] op_sel_hi:[0,1]
	v_pk_mul_f32 v[8:9], v[80:81], v[8:9]
	v_pk_mul_f32 v[16:17], v[0:1], v[16:17] op_sel_hi:[0,1]
	v_cvt_pk_bf16_f32 v158, v12, v13
	v_pk_mul_f32 v[2:3], v[76:77], v[2:3]
	v_pk_mul_f32 v[12:13], v[72:73], v[8:9]
	v_pk_mul_f32 v[16:17], v[92:93], v[16:17]
	v_cvt_pk_bf16_f32 v149, v14, v15
	v_pk_fma_f32 v[12:13], v[68:69], v[2:3], v[12:13] neg_lo:[0,0,1] neg_hi:[0,0,1]
	v_pk_mul_f32 v[2:3], v[72:73], v[2:3]
	v_lshlrev_b32_e32 v14, 16, v36
	v_and_b32_e32 v15, 0xffff0000, v36
	v_pk_fma_f32 v[22:23], v[84:85], v[16:17], v[22:23] neg_lo:[0,0,1] neg_hi:[0,0,1]
	v_pk_mul_f32 v[16:17], v[88:89], v[16:17]
	v_pk_fma_f32 v[2:3], v[68:69], v[8:9], v[2:3]
	v_lshlrev_b32_e32 v8, 16, v4
	v_and_b32_e32 v9, 0xffff0000, v4
	v_pk_mul_f32 v[14:15], v[0:1], v[14:15] op_sel_hi:[0,1]
	v_pk_fma_f32 v[16:17], v[84:85], v[20:21], v[16:17]
	v_pk_mul_f32 v[8:9], v[0:1], v[8:9] op_sel_hi:[0,1]
	v_pk_mul_f32 v[14:15], v[62:63], v[14:15]
	v_cvt_pk_bf16_f32 v159, v16, v17
	v_pk_mul_f32 v[8:9], v[58:59], v[8:9]
	v_pk_mul_f32 v[16:17], v[54:55], v[14:15]
	v_lshlrev_b32_e32 v4, 16, v5
	v_pk_fma_f32 v[16:17], v[50:51], v[8:9], v[16:17] neg_lo:[0,0,1] neg_hi:[0,0,1]
	v_pk_mul_f32 v[8:9], v[54:55], v[8:9]
	v_and_b32_e32 v5, 0xffff0000, v5
	v_pk_fma_f32 v[8:9], v[50:51], v[14:15], v[8:9]
	v_lshlrev_b32_e32 v14, 16, v37
	v_and_b32_e32 v15, 0xffff0000, v37
	v_pk_mul_f32 v[14:15], v[0:1], v[14:15] op_sel_hi:[0,1]
	v_pk_mul_f32 v[4:5], v[0:1], v[4:5] op_sel_hi:[0,1]
	v_pk_mul_f32 v[14:15], v[64:65], v[14:15]
	v_cvt_pk_bf16_f32 v150, v18, v19
	v_pk_mul_f32 v[4:5], v[60:61], v[4:5]
	v_pk_mul_f32 v[18:19], v[56:57], v[14:15]
	v_cvt_pk_bf16_f32 v177, v2, v3
	v_lshlrev_b32_e32 v2, 1, v228
	v_lshrrev_b32_e32 v3, 1, v231
	v_pk_fma_f32 v[18:19], v[52:53], v[4:5], v[18:19] neg_lo:[0,0,1] neg_hi:[0,0,1]
	v_pk_mul_f32 v[4:5], v[56:57], v[4:5]
	v_and_b32_e32 v0, 19, v231
	v_and_b32_e32 v2, 8, v2
	v_and_b32_e32 v3, 4, v3
	v_pk_fma_f32 v[4:5], v[52:53], v[14:15], v[4:5]
	v_or3_b32 v0, v0, v2, v3
	v_mov_b32_e32 v14, v1
	v_mov_b32_e32 v15, v1
	v_cvt_pk_bf16_f32 v151, v22, v23
	v_cvt_pk_bf16_f32 v168, v10, v11
	v_cvt_pk_bf16_f32 v169, v12, v13
	v_cvt_pk_bf16_f32 v170, v16, v17
	v_cvt_pk_bf16_f32 v171, v18, v19
	v_cvt_pk_bf16_f32 v176, v6, v7
	v_cvt_pk_bf16_f32 v178, v8, v9
	v_cvt_pk_bf16_f32 v179, v4, v5
	v_mul_u32_u24_e32 v180, 0x190, v0
	v_mov_b32_e32 v0, v1
	v_mov_b32_e32 v2, v1
	v_mov_b32_e32 v3, v1
	v_mov_b32_e32 v4, v1
	v_mov_b32_e32 v5, v1
	v_mov_b32_e32 v6, v1
	v_mov_b32_e32 v7, v1
	v_mov_b32_e32 v8, v1
	v_mov_b32_e32 v9, v1
	v_mov_b32_e32 v10, v1
	v_mov_b32_e32 v11, v1
	v_mov_b32_e32 v12, v1
	v_mov_b32_e32 v13, v1
	v_mov_b64_e32 v[30:31], v[14:15]
	v_mov_b64_e32 v[46:47], v[14:15]
	v_mov_b64_e32 v[62:63], v[14:15]
	v_mov_b64_e32 v[78:79], v[14:15]
	s_mov_b32 s11, 0
	v_mov_b32_e32 v182, 0
	v_mov_b64_e32 v[28:29], v[12:13]
	v_mov_b64_e32 v[26:27], v[10:11]
	v_mov_b64_e32 v[24:25], v[8:9]
	v_mov_b64_e32 v[22:23], v[6:7]
	v_mov_b64_e32 v[20:21], v[4:5]
	v_mov_b64_e32 v[18:19], v[2:3]
	v_mov_b64_e32 v[16:17], v[0:1]
	v_mov_b64_e32 v[44:45], v[12:13]
	v_mov_b64_e32 v[42:43], v[10:11]
	v_mov_b64_e32 v[40:41], v[8:9]
	v_mov_b64_e32 v[38:39], v[6:7]
	v_mov_b64_e32 v[36:37], v[4:5]
	v_mov_b64_e32 v[34:35], v[2:3]
	v_mov_b64_e32 v[32:33], v[0:1]
	v_mov_b64_e32 v[60:61], v[12:13]
	v_mov_b64_e32 v[58:59], v[10:11]
	v_mov_b64_e32 v[56:57], v[8:9]
	v_mov_b64_e32 v[54:55], v[6:7]
	v_mov_b64_e32 v[52:53], v[4:5]
	v_mov_b64_e32 v[50:51], v[2:3]
	v_mov_b64_e32 v[48:49], v[0:1]
	v_mov_b64_e32 v[76:77], v[12:13]
	v_mov_b64_e32 v[74:75], v[10:11]
	v_mov_b64_e32 v[72:73], v[8:9]
	v_mov_b64_e32 v[70:71], v[6:7]
	v_mov_b64_e32 v[68:69], v[4:5]
	v_mov_b64_e32 v[66:67], v[2:3]
	v_mov_b64_e32 v[64:65], v[0:1]
	s_mov_b32 s100, 0
	s_mov_b32 s101, 0xac00
.LBB0_631:
	s_add_i32 s10, s11, 1
	s_cmp_gt_i32 s11, s1
	s_cbranch_scc1 .Lattn1_stage_only
	v_add3_u32 v0, s100, v180, v229
	ds_read_b128 v[2:5], v0
	ds_read_b128 v[6:9], v0 offset:32
	ds_read_b128 v[10:13], v0 offset:64
	ds_read_b128 v[184:187], v0 offset:96
	ds_read_b128 v[188:191], v0 offset:128
	ds_read_b128 v[192:195], v0 offset:160
	ds_read_b128 v[196:199], v0 offset:192
	s_mov_b32 s16, s101
	v_add_u32_e32 v247, s16, v233
	v_add_u32_e32 v248, s16, v234
	v_add_u32_e32 v249, s16, v236
	v_add_u32_e32 v250, s16, v208
	v_add_u32_e32 v251, s16, v200
	s_cmp_lt_u32 s11, s7
	s_cselect_b64 s[16:17], -1, 0
	s_cmp_lg_u64 s[16:17], 0
	s_addc_u32 s6, s6, 0
	s_mov_b32 s22, s14
	s_mov_b32 s23, s15
	s_mov_b32 s26, s14
	s_mov_b32 s27, s15
	v_mov_b32_e32 v80, v213
	v_mov_b32_e32 v81, v80
	v_mov_b32_e32 v82, v80
	v_mov_b32_e32 v83, v80
	v_mov_b32_e32 v84, v80
	v_mov_b32_e32 v85, v80
	v_mov_b32_e32 v86, v80
	v_mov_b32_e32 v87, v80
	v_mov_b32_e32 v88, v80
	v_mov_b32_e32 v89, v80
	v_mov_b32_e32 v90, v80
	v_mov_b32_e32 v91, v80
	v_mov_b32_e32 v92, v80
	v_mov_b32_e32 v93, v80
	v_mov_b32_e32 v94, v80
	v_mov_b32_e32 v95, v80
	s_mov_b32 s11, s100
	s_waitcnt lgkmcnt(6)
	v_mfma_f32_32x32x16_bf16 v[96:111], v[2:5], v[132:135], v[80:95]
	s_mul_i32 s16, s6, 0x6000
	s_waitcnt vmcnt(4)
	ds_write_b128 v247, v[112:115]
	buffer_load_dwordx4 v[112:115], v230, s[20:23], s16 offen
	ds_read_b128 v[2:5], v0 offset:224
	s_waitcnt lgkmcnt(6)
	v_mfma_f32_32x32x16_bf16 v[96:111], v[6:9], v[136:139], v[96:111]
	ds_read_b128 v[6:9], v0 offset:256
	s_waitcnt lgkmcnt(6)
	v_mfma_f32_32x32x16_bf16 v[96:111], v[10:13], v[140:143], v[96:111]
	s_add_i32 s17, s16, 0x2000
	s_waitcnt vmcnt(4)
	ds_write_b128 v248, v[116:119]
	buffer_load_dwordx4 v[116:119], v230, s[20:23], s17 offen
	ds_read_b128 v[10:13], v0 offset:288
	s_waitcnt lgkmcnt(6)
	v_mfma_f32_32x32x16_bf16 v[96:111], v[184:187], v[144:147], v[96:111]
	ds_read_b128 v[184:187], v0 offset:320
	s_waitcnt lgkmcnt(6)
	v_mfma_f32_32x32x16_bf16 v[96:111], v[188:191], v[152:155], v[96:111]
	s_addk_i32 s16, 0x4000
	s_waitcnt vmcnt(4)
	ds_write_b128 v249, v[120:123]
	buffer_load_dwordx4 v[120:123], v230, s[20:23], s16 offen
	ds_read_b128 v[188:191], v0 offset:352
	s_waitcnt lgkmcnt(6)
	v_mfma_f32_32x32x16_bf16 v[96:111], v[192:195], v[164:167], v[96:111]
	ds_read_b128 v[192:195], v0 offset:12800
	s_waitcnt lgkmcnt(6)
	v_mfma_f32_32x32x16_bf16 v[96:111], v[196:199], v[172:175], v[96:111]
	s_lshl_b32 s16, s6, 7
	s_waitcnt vmcnt(4)
	ds_write_b128 v250, v[124:127] offset:25600
	buffer_load_dwordx4 v[124:127], v232, s[24:27], s16 offen
	ds_read_b128 v[196:199], v0 offset:12832
	s_waitcnt lgkmcnt(6)
	v_mfma_f32_32x32x16_bf16 v[96:111], v[2:5], v[160:163], v[96:111]
	ds_read_b128 v[2:5], v0 offset:12864
	s_waitcnt lgkmcnt(6)
	v_mfma_f32_32x32x16_bf16 v[96:111], v[6:9], v[148:151], v[96:111]
	s_add_i32 s16, s16, 0x100000
	s_waitcnt vmcnt(4)
	ds_write_b128 v251, v[128:131] offset:25600
	buffer_load_dwordx4 v[128:131], v232, s[24:27], s16 offen
	ds_read_b128 v[6:9], v0 offset:12896
	s_waitcnt lgkmcnt(6)
	v_mfma_f32_32x32x16_bf16 v[96:111], v[10:13], v[168:171], v[96:111]
	ds_read_b128 v[10:13], v0 offset:12928
	s_waitcnt lgkmcnt(6)
	v_mfma_f32_32x32x16_bf16 v[96:111], v[184:187], v[156:159], v[96:111]
	ds_read_b128 v[184:187], v0 offset:12960
	s_waitcnt lgkmcnt(6)
	v_mfma_f32_32x32x16_bf16 v[96:111], v[188:191], v[176:179], v[96:111]
	ds_read_b128 v[188:191], v0 offset:12992
	s_waitcnt lgkmcnt(6)
	v_mfma_f32_32x32x16_bf16 v[80:95], v[192:195], v[132:135], v[80:95]
	s_nop 8
	v_exp_f32_e32 v206, v96
	v_exp_f32_e32 v207, v97
	ds_read_b128 v[192:195], v0 offset:13024
	s_waitcnt lgkmcnt(6)
	v_mfma_f32_32x32x16_bf16 v[80:95], v[196:199], v[136:139], v[80:95]
	v_add_f32_e32 v14, v207, v206
	v_add_f32_e32 v96, v182, v14
	ds_read_b128 v[196:199], v0 offset:13056
	s_waitcnt lgkmcnt(6)
	v_mfma_f32_32x32x16_bf16 v[80:95], v[2:5], v[140:143], v[80:95]
	v_exp_f32_e32 v15, v98
	v_exp_f32_e32 v183, v99
	v_exp_f32_e32 v14, v100
	v_exp_f32_e32 v182, v101
	ds_read_b128 v[2:5], v0 offset:13088
	s_waitcnt lgkmcnt(6)
	v_mfma_f32_32x32x16_bf16 v[80:95], v[6:9], v[144:147], v[80:95]
	v_add_f32_e64 v6, v182, v14
	v_add_f32_e64 v7, v183, v15
	v_add_f32_e32 v7, v7, v96
	v_add_f32_e32 v98, v6, v7
	ds_read_b128 v[6:9], v0 offset:13120
	s_waitcnt lgkmcnt(6)
	v_mfma_f32_32x32x16_bf16 v[80:95], v[10:13], v[152:155], v[80:95]
	v_exp_f32_e32 v203, v102
	v_exp_f32_e32 v205, v103
	v_exp_f32_e32 v202, v104
	v_exp_f32_e32 v204, v105
	ds_read_b128 v[10:13], v0 offset:13152
	s_waitcnt lgkmcnt(6)
	v_mfma_f32_32x32x16_bf16 v[80:95], v[184:187], v[164:167], v[80:95]
	v_add_f32_e64 v96, v204, v202
	v_add_f32_e64 v97, v205, v203
	v_add_f32_e32 v0, v97, v98
	v_add_f32_e32 v0, v96, v0
	v_add3_u32 v209, s11, v181, v229
	ds_read_b128 v[96:99], v209 offset:25600
	s_waitcnt lgkmcnt(6)
	v_mfma_f32_32x32x16_bf16 v[80:95], v[188:191], v[172:175], v[80:95]
	v_exp_f32_e32 v187, v106
	v_exp_f32_e32 v189, v107
	v_exp_f32_e32 v186, v108
	v_exp_f32_e32 v188, v109
	ds_read_b128 v[100:103], v209 offset:30208
	s_waitcnt lgkmcnt(6)
	v_mfma_f32_32x32x16_bf16 v[80:95], v[192:195], v[160:163], v[80:95]
	v_add_f32_e64 v104, v188, v186
	v_add_f32_e64 v105, v189, v187
	v_add_f32_e32 v0, v105, v0
	v_add_f32_e32 v190, v104, v0
	ds_read_b128 v[104:107], v209 offset:34816
	s_waitcnt lgkmcnt(6)
	v_mfma_f32_32x32x16_bf16 v[80:95], v[196:199], v[148:151], v[80:95]
	s_barrier
	v_exp_f32_e32 v192, v110
	v_exp_f32_e32 v194, v111
	ds_read_b128 v[108:111], v209 offset:39424
	s_waitcnt lgkmcnt(6)
	v_mfma_f32_32x32x16_bf16 v[80:95], v[2:5], v[168:171], v[80:95]
	v_cvt_pk_bf16_f32 v2, v206, v207
	v_cvt_pk_bf16_f32 v3, v15, v183
	v_cvt_pk_bf16_f32 v4, v14, v182
	v_cvt_pk_bf16_f32 v5, v203, v205
	ds_read_b128 v[182:185], v209 offset:25632
	s_waitcnt lgkmcnt(6)
	v_mfma_f32_32x32x16_bf16 v[80:95], v[6:9], v[156:159], v[80:95]
	v_cvt_pk_bf16_f32 v6, v202, v204
	v_cvt_pk_bf16_f32 v7, v187, v189
	v_cvt_pk_bf16_f32 v8, v186, v188
	ds_read_b128 v[186:189], v209 offset:30240
	s_waitcnt lgkmcnt(6)
	v_mfma_f32_32x32x16_bf16 v[80:95], v[10:13], v[176:179], v[80:95]
	s_waitcnt lgkmcnt(5)
	v_mfma_f32_32x32x16_bf16 v[64:79], v[96:99], v[2:5], v[64:79]
	ds_read_b128 v[10:13], v209 offset:34848
	s_waitcnt lgkmcnt(5)
	v_mfma_f32_32x32x16_bf16 v[48:63], v[100:103], v[2:5], v[48:63]
	s_nop 6
	v_exp_f32_e32 v195, v80
	v_exp_f32_e32 v193, v81
	ds_read_b128 v[96:99], v209 offset:39456
	v_exp_f32_e32 v191, v82
	v_cvt_pk_bf16_f32 v9, v192, v194
	v_pk_add_f32 v[14:15], v[194:195], v[192:193]
	s_nop 0
	v_pk_add_f32 v[14:15], v[190:191], v[14:15]
	s_waitcnt lgkmcnt(5)
	v_mfma_f32_32x32x16_bf16 v[32:47], v[104:107], v[2:5], v[32:47]
	ds_read_b128 v[100:103], v209 offset:25664
	v_exp_f32_e32 v0, v83
	v_exp_f32_e32 v190, v84
	v_exp_f32_e32 v105, v85
	v_add_f32_e32 v107, v0, v190
	s_waitcnt lgkmcnt(5)
	v_mfma_f32_32x32x16_bf16 v[16:31], v[108:111], v[2:5], v[16:31]
	ds_read_b128 v[80:83], v209 offset:30272
	v_exp_f32_e32 v106, v86
	v_exp_f32_e32 v104, v87
	s_nop 0
	v_pk_add_f32 v[108:109], v[104:105], v[106:107]
	s_waitcnt lgkmcnt(5)
	v_mfma_f32_32x32x16_bf16 v[64:79], v[182:185], v[6:9], v[64:79]
	ds_read_b128 v[2:5], v209 offset:34880
	v_exp_f32_e32 v111, v88
	v_exp_f32_e32 v185, v89
	s_waitcnt lgkmcnt(5)
	v_mfma_f32_32x32x16_bf16 v[48:63], v[186:189], v[6:9], v[48:63]
	v_exp_f32_e32 v110, v90
	v_exp_f32_e32 v184, v91
	ds_read_b128 v[84:87], v209 offset:39488
	v_pk_add_f32 v[182:183], v[184:185], v[110:111]
	s_waitcnt lgkmcnt(5)
	v_mfma_f32_32x32x16_bf16 v[32:47], v[10:13], v[6:9], v[32:47]
	ds_read_b128 v[88:91], v209 offset:25696
	v_exp_f32_e32 v187, v92
	v_exp_f32_e32 v189, v93
	s_waitcnt lgkmcnt(5)
	v_mfma_f32_32x32x16_bf16 v[16:31], v[96:99], v[6:9], v[16:31]
	v_exp_f32_e32 v186, v94
	v_exp_f32_e32 v188, v95
	v_add_f32_e32 v92, v14, v15
	v_add_f32_e32 v92, v109, v92
	v_add_f32_e32 v6, v108, v92
	ds_read_b128 v[10:13], v209 offset:30304
	v_add_f32_e32 v6, v183, v6
	v_pk_add_f32 v[14:15], v[188:189], v[186:187]
	v_add_f32_e32 v6, v182, v6
	v_add_f32_e32 v6, v15, v6
	v_add_f32_e32 v182, v14, v6
	v_cvt_pk_bf16_f32 v6, v195, v193
	v_cvt_pk_bf16_f32 v7, v191, v0
	v_cvt_pk_bf16_f32 v8, v190, v105
	v_cvt_pk_bf16_f32 v9, v106, v104
	v_cvt_pk_bf16_f32 v92, v111, v185
	v_cvt_pk_bf16_f32 v93, v110, v184
	v_cvt_pk_bf16_f32 v94, v187, v189
	v_cvt_pk_bf16_f32 v95, v186, v188
	s_waitcnt lgkmcnt(5)
	v_mfma_f32_32x32x16_bf16 v[64:79], v[100:103], v[6:9], v[64:79]
	ds_read_b128 v[96:99], v209 offset:34912
	s_waitcnt lgkmcnt(5)
	v_mfma_f32_32x32x16_bf16 v[48:63], v[80:83], v[6:9], v[48:63]
	ds_read_b128 v[100:103], v209 offset:39520
	s_waitcnt lgkmcnt(5)
	v_mfma_f32_32x32x16_bf16 v[32:47], v[2:5], v[6:9], v[32:47]
	s_waitcnt lgkmcnt(4)
	v_mfma_f32_32x32x16_bf16 v[16:31], v[84:87], v[6:9], v[16:31]
	s_waitcnt lgkmcnt(3)
	v_mfma_f32_32x32x16_bf16 v[64:79], v[88:91], v[92:95], v[64:79]
	s_waitcnt lgkmcnt(2)
	v_mfma_f32_32x32x16_bf16 v[48:63], v[10:13], v[92:95], v[48:63]
	s_waitcnt lgkmcnt(1)
	v_mfma_f32_32x32x16_bf16 v[32:47], v[96:99], v[92:95], v[32:47]
	s_waitcnt lgkmcnt(0)
	v_mfma_f32_32x32x16_bf16 v[16:31], v[100:103], v[92:95], v[16:31]
.LBB0_633:
	s_mov_b32 s100, s101
	s_add_i32 s101, s101, 0xac00
	s_cmp_eq_u32 s101, 0x20400
	s_cselect_b32 s101, 0, s101
	s_cmp_eq_u32 s9, s10
	s_waitcnt lgkmcnt(0)
	s_cbranch_scc1 .Lattn1_exit
	s_mov_b32 s11, s10
	s_branch .LBB0_631
.Lattn1_stage_only:
	s_mov_b32 s16, s101
	v_add_u32_e32 v247, s16, v233
	v_add_u32_e32 v248, s16, v234
	v_add_u32_e32 v249, s16, v236
	v_add_u32_e32 v250, s16, v208
	v_add_u32_e32 v251, s16, v200
	s_cmp_lt_u32 s11, s7
	s_cselect_b64 s[16:17], -1, 0
	s_cmp_lg_u64 s[16:17], 0
	s_addc_u32 s6, s6, 0
	s_mov_b32 s22, s14
	s_mov_b32 s23, s15
	s_mov_b32 s26, s14
	s_mov_b32 s27, s15
	s_mul_i32 s16, s6, 0x6000
	s_waitcnt vmcnt(4)
	ds_write_b128 v247, v[112:115]
	buffer_load_dwordx4 v[112:115], v230, s[20:23], s16 offen
	s_add_i32 s17, s16, 0x2000
	s_waitcnt vmcnt(4)
	ds_write_b128 v248, v[116:119]
	buffer_load_dwordx4 v[116:119], v230, s[20:23], s17 offen
	s_addk_i32 s16, 0x4000
	s_waitcnt vmcnt(4)
	ds_write_b128 v249, v[120:123]
	buffer_load_dwordx4 v[120:123], v230, s[20:23], s16 offen
	s_lshl_b32 s16, s6, 7
	s_waitcnt vmcnt(4)
	ds_write_b128 v250, v[124:127] offset:25600
	buffer_load_dwordx4 v[124:127], v232, s[24:27], s16 offen
	s_add_i32 s16, s16, 0x100000
	s_waitcnt vmcnt(4)
	ds_write_b128 v251, v[128:131] offset:25600
	buffer_load_dwordx4 v[128:131], v232, s[24:27], s16 offen
	s_waitcnt lgkmcnt(0)
	s_barrier
	s_branch .LBB0_633

.LBB0_708:
	v_rsq_f32_e32 v0, v0
	v_and_b32_e32 v111, 0xffff0000, v42
	s_lshl_b32 s8, s1, 2
	s_ashr_i32 s1, s6, 7
	v_mul_f32_e32 v110, 0x45800000, v0
	v_cndmask_b32_e32 v0, v0, v110, vcc
	v_mul_f32_e32 v0, v230, v0
	v_mul_f32_e32 v0, 0x3dd53b94, v0
	v_lshlrev_b32_e32 v110, 16, v42
	v_lshlrev_b32_e32 v42, 16, v43
	v_and_b32_e32 v43, 0xffff0000, v43
	v_pk_mul_f32 v[42:43], v[0:1], v[42:43] op_sel_hi:[0,1]
	v_pk_mul_f32 v[110:111], v[0:1], v[110:111] op_sel_hi:[0,1]
	v_pk_mul_f32 v[42:43], v[134:135], v[42:43]
	v_pk_mul_f32 v[110:111], v[132:133], v[110:111]
	v_cvt_pk_bf16_f32 v133, v42, v43
	v_lshlrev_b32_e32 v42, 16, v44
	v_and_b32_e32 v43, 0xffff0000, v44
	v_pk_mul_f32 v[42:43], v[0:1], v[42:43] op_sel_hi:[0,1]
	v_pk_mul_f32 v[42:43], v[196:197], v[42:43]
	v_lshlrev_b32_e32 v201, 3, v231
	v_cvt_pk_bf16_f32 v134, v42, v43
	v_lshlrev_b32_e32 v42, 16, v45
	v_and_b32_e32 v43, 0xffff0000, v45
	v_pk_mul_f32 v[42:43], v[0:1], v[42:43] op_sel_hi:[0,1]
	v_pk_mul_f32 v[42:43], v[198:199], v[42:43]
	v_cvt_pk_bf16_f32 v132, v110, v111
	v_cvt_pk_bf16_f32 v135, v42, v43
	v_lshlrev_b32_e32 v42, 16, v18
	v_and_b32_e32 v43, 0xffff0000, v18
	v_lshlrev_b32_e32 v18, 16, v19
	v_and_b32_e32 v19, 0xffff0000, v19
	v_pk_mul_f32 v[18:19], v[0:1], v[18:19] op_sel_hi:[0,1]
	v_pk_mul_f32 v[42:43], v[0:1], v[42:43] op_sel_hi:[0,1]
	v_pk_mul_f32 v[18:19], v[138:139], v[18:19]
	v_pk_mul_f32 v[42:43], v[136:137], v[42:43]
	v_cvt_pk_bf16_f32 v137, v18, v19
	v_lshlrev_b32_e32 v18, 16, v20
	v_and_b32_e32 v19, 0xffff0000, v20
	v_pk_mul_f32 v[18:19], v[0:1], v[18:19] op_sel_hi:[0,1]
	v_pk_mul_f32 v[18:19], v[192:193], v[18:19]
	v_cvt_pk_bf16_f32 v136, v42, v43
	v_cvt_pk_bf16_f32 v138, v18, v19
	v_lshlrev_b32_e32 v18, 16, v21
	v_and_b32_e32 v19, 0xffff0000, v21
	v_pk_mul_f32 v[18:19], v[0:1], v[18:19] op_sel_hi:[0,1]
	v_pk_mul_f32 v[18:19], v[194:195], v[18:19]
	s_add_i32 s1, s1, s8
	v_cvt_pk_bf16_f32 v139, v18, v19
	v_lshlrev_b32_e32 v18, 16, v38
	v_and_b32_e32 v19, 0xffff0000, v38
	v_pk_mul_f32 v[18:19], v[0:1], v[18:19] op_sel_hi:[0,1]
	v_pk_mul_f32 v[18:19], v[140:141], v[18:19]
	s_mov_b32 s6, 1
	v_cvt_pk_bf16_f32 v140, v18, v19
	v_lshlrev_b32_e32 v18, 16, v39
	v_and_b32_e32 v19, 0xffff0000, v39
	v_pk_mul_f32 v[18:19], v[0:1], v[18:19] op_sel_hi:[0,1]
	v_pk_mul_f32 v[18:19], v[142:143], v[18:19]
	s_or_b32 s7, s8, 2
	v_cvt_pk_bf16_f32 v141, v18, v19
	v_lshlrev_b32_e32 v18, 16, v40
	v_and_b32_e32 v19, 0xffff0000, v40
	v_pk_mul_f32 v[18:19], v[0:1], v[18:19] op_sel_hi:[0,1]
	v_pk_mul_f32 v[18:19], v[188:189], v[18:19]
	s_add_i32 s8, s8, 4
	v_cvt_pk_bf16_f32 v142, v18, v19
	v_lshlrev_b32_e32 v18, 16, v41
	v_and_b32_e32 v19, 0xffff0000, v41
	v_pk_mul_f32 v[18:19], v[0:1], v[18:19] op_sel_hi:[0,1]
	v_pk_mul_f32 v[18:19], v[190:191], v[18:19]
	s_mov_b32 s10, 0
	v_cvt_pk_bf16_f32 v143, v18, v19
	v_lshlrev_b32_e32 v18, 16, v26
	v_and_b32_e32 v19, 0xffff0000, v26
	v_pk_mul_f32 v[18:19], v[0:1], v[18:19] op_sel_hi:[0,1]
	v_pk_mul_f32 v[18:19], v[144:145], v[18:19]
	s_nop 0
	v_cvt_pk_bf16_f32 v144, v18, v19
	v_lshlrev_b32_e32 v18, 16, v27
	v_and_b32_e32 v19, 0xffff0000, v27
	v_pk_mul_f32 v[18:19], v[0:1], v[18:19] op_sel_hi:[0,1]
	v_pk_mul_f32 v[18:19], v[146:147], v[18:19]
	s_nop 0
	v_cvt_pk_bf16_f32 v145, v18, v19
	v_lshlrev_b32_e32 v18, 16, v28
	v_and_b32_e32 v19, 0xffff0000, v28
	v_pk_mul_f32 v[18:19], v[0:1], v[18:19] op_sel_hi:[0,1]
	v_pk_mul_f32 v[18:19], v[184:185], v[18:19]
	s_nop 0
	v_cvt_pk_bf16_f32 v146, v18, v19
	v_lshlrev_b32_e32 v18, 16, v29
	v_and_b32_e32 v19, 0xffff0000, v29
	v_pk_mul_f32 v[18:19], v[0:1], v[18:19] op_sel_hi:[0,1]
	v_pk_mul_f32 v[18:19], v[186:187], v[18:19]
	s_nop 0
	v_cvt_pk_bf16_f32 v147, v18, v19
	v_lshlrev_b32_e32 v18, 16, v34
	v_and_b32_e32 v19, 0xffff0000, v34
	v_pk_mul_f32 v[18:19], v[0:1], v[18:19] op_sel_hi:[0,1]
	v_pk_mul_f32 v[18:19], v[148:149], v[18:19]
	s_nop 0
	v_cvt_pk_bf16_f32 v148, v18, v19
	v_lshlrev_b32_e32 v18, 16, v35
	v_and_b32_e32 v19, 0xffff0000, v35
	v_pk_mul_f32 v[18:19], v[0:1], v[18:19] op_sel_hi:[0,1]
	v_pk_mul_f32 v[18:19], v[150:151], v[18:19]
	s_nop 0
	v_cvt_pk_bf16_f32 v149, v18, v19
	v_lshlrev_b32_e32 v18, 16, v36
	v_and_b32_e32 v19, 0xffff0000, v36
	v_pk_mul_f32 v[18:19], v[0:1], v[18:19] op_sel_hi:[0,1]
	v_pk_mul_f32 v[18:19], v[180:181], v[18:19]
	v_mul_u32_u24_e32 v181, 0x90, v205
	v_cvt_pk_bf16_f32 v150, v18, v19
	v_lshlrev_b32_e32 v18, 16, v37
	v_and_b32_e32 v19, 0xffff0000, v37
	v_pk_mul_f32 v[18:19], v[0:1], v[18:19] op_sel_hi:[0,1]
	v_pk_mul_f32 v[18:19], v[182:183], v[18:19]
	v_mov_b32_e32 v182, 0
	v_cvt_pk_bf16_f32 v151, v18, v19
	v_lshlrev_b32_e32 v18, 16, v22
	v_and_b32_e32 v19, 0xffff0000, v22
	v_pk_mul_f32 v[18:19], v[0:1], v[18:19] op_sel_hi:[0,1]
	v_pk_mul_f32 v[18:19], v[152:153], v[18:19]
	v_lshlrev_b32_e32 v22, 16, v48
	v_cvt_pk_bf16_f32 v152, v18, v19
	v_lshlrev_b32_e32 v18, 16, v23
	v_and_b32_e32 v19, 0xffff0000, v23
	v_pk_mul_f32 v[18:19], v[0:1], v[18:19] op_sel_hi:[0,1]
	v_pk_mul_f32 v[18:19], v[154:155], v[18:19]
	v_and_b32_e32 v23, 0xffff0000, v48
	v_cvt_pk_bf16_f32 v153, v18, v19
	v_lshlrev_b32_e32 v18, 16, v24
	v_and_b32_e32 v19, 0xffff0000, v24
	v_pk_mul_f32 v[18:19], v[0:1], v[18:19] op_sel_hi:[0,1]
	v_pk_mul_f32 v[18:19], v[176:177], v[18:19]
	v_pk_mul_f32 v[22:23], v[0:1], v[22:23] op_sel_hi:[0,1]
	v_cvt_pk_bf16_f32 v154, v18, v19
	v_lshlrev_b32_e32 v18, 16, v25
	v_and_b32_e32 v19, 0xffff0000, v25
	v_pk_mul_f32 v[18:19], v[0:1], v[18:19] op_sel_hi:[0,1]
	v_pk_mul_f32 v[18:19], v[178:179], v[18:19]
	v_pk_mul_f32 v[22:23], v[94:95], v[22:23]
	v_cvt_pk_bf16_f32 v155, v18, v19
	v_lshlrev_b32_e32 v18, 16, v30
	v_and_b32_e32 v19, 0xffff0000, v30
	v_pk_mul_f32 v[18:19], v[0:1], v[18:19] op_sel_hi:[0,1]
	v_pk_mul_f32 v[18:19], v[156:157], v[18:19]
	v_pk_mul_f32 v[24:25], v[86:87], v[22:23]
	v_cvt_pk_bf16_f32 v156, v18, v19
	v_lshlrev_b32_e32 v18, 16, v31
	v_and_b32_e32 v19, 0xffff0000, v31
	v_pk_mul_f32 v[18:19], v[0:1], v[18:19] op_sel_hi:[0,1]
	v_pk_mul_f32 v[18:19], v[158:159], v[18:19]
	s_nop 0
	v_cvt_pk_bf16_f32 v157, v18, v19
	v_lshlrev_b32_e32 v18, 16, v32
	v_and_b32_e32 v19, 0xffff0000, v32
	v_pk_mul_f32 v[18:19], v[0:1], v[18:19] op_sel_hi:[0,1]
	v_pk_mul_f32 v[18:19], v[172:173], v[18:19]
	s_nop 0
	v_cvt_pk_bf16_f32 v158, v18, v19
	v_lshlrev_b32_e32 v18, 16, v33
	v_and_b32_e32 v19, 0xffff0000, v33
	v_pk_mul_f32 v[18:19], v[0:1], v[18:19] op_sel_hi:[0,1]
	v_pk_mul_f32 v[18:19], v[174:175], v[18:19]
	s_nop 0
	v_cvt_pk_bf16_f32 v159, v18, v19
	v_lshlrev_b32_e32 v18, 16, v14
	v_and_b32_e32 v19, 0xffff0000, v14
	v_lshlrev_b32_e32 v14, 16, v15
	v_and_b32_e32 v15, 0xffff0000, v15
	v_pk_mul_f32 v[14:15], v[0:1], v[14:15] op_sel_hi:[0,1]
	v_pk_mul_f32 v[18:19], v[0:1], v[18:19] op_sel_hi:[0,1]
	v_pk_mul_f32 v[14:15], v[162:163], v[14:15]
	v_pk_mul_f32 v[18:19], v[160:161], v[18:19]
	v_cvt_pk_bf16_f32 v161, v14, v15
	v_lshlrev_b32_e32 v14, 16, v16
	v_and_b32_e32 v15, 0xffff0000, v16
	v_pk_mul_f32 v[14:15], v[0:1], v[14:15] op_sel_hi:[0,1]
	v_pk_mul_f32 v[14:15], v[168:169], v[14:15]
	v_lshlrev_b32_e32 v16, 16, v46
	v_cvt_pk_bf16_f32 v162, v14, v15
	v_lshlrev_b32_e32 v14, 16, v17
	v_and_b32_e32 v15, 0xffff0000, v17
	v_pk_mul_f32 v[14:15], v[0:1], v[14:15] op_sel_hi:[0,1]
	v_pk_mul_f32 v[14:15], v[170:171], v[14:15]
	v_and_b32_e32 v17, 0xffff0000, v46
	v_cvt_pk_bf16_f32 v163, v14, v15
	v_lshlrev_b32_e32 v14, 16, v6
	v_and_b32_e32 v15, 0xffff0000, v6
	v_pk_mul_f32 v[16:17], v[0:1], v[16:17] op_sel_hi:[0,1]
	v_pk_mul_f32 v[14:15], v[0:1], v[14:15] op_sel_hi:[0,1]
	v_pk_mul_f32 v[16:17], v[164:165], v[16:17]
	v_cvt_pk_bf16_f32 v160, v18, v19
	v_pk_mul_f32 v[14:15], v[106:107], v[14:15]
	v_pk_mul_f32 v[18:19], v[102:103], v[16:17]
	v_lshlrev_b32_e32 v6, 16, v7
	v_pk_fma_f32 v[18:19], v[98:99], v[14:15], v[18:19] neg_lo:[0,0,1] neg_hi:[0,0,1]
	v_pk_mul_f32 v[14:15], v[102:103], v[14:15]
	v_and_b32_e32 v7, 0xffff0000, v7
	v_pk_fma_f32 v[14:15], v[98:99], v[16:17], v[14:15]
	v_lshlrev_b32_e32 v16, 16, v47
	v_and_b32_e32 v17, 0xffff0000, v47
	v_pk_mul_f32 v[16:17], v[0:1], v[16:17] op_sel_hi:[0,1]
	v_pk_mul_f32 v[6:7], v[0:1], v[6:7] op_sel_hi:[0,1]
	v_pk_mul_f32 v[16:17], v[166:167], v[16:17]
	v_pk_mul_f32 v[6:7], v[108:109], v[6:7]
	v_pk_mul_f32 v[20:21], v[104:105], v[16:17]
	v_cvt_pk_bf16_f32 v168, v14, v15
	v_pk_fma_f32 v[20:21], v[100:101], v[6:7], v[20:21] neg_lo:[0,0,1] neg_hi:[0,0,1]
	v_pk_mul_f32 v[6:7], v[104:105], v[6:7]
	v_cvt_pk_bf16_f32 v164, v18, v19
	v_pk_fma_f32 v[6:7], v[100:101], v[16:17], v[6:7]
	v_lshlrev_b32_e32 v16, 16, v8
	v_and_b32_e32 v17, 0xffff0000, v8
	v_pk_mul_f32 v[16:17], v[0:1], v[16:17] op_sel_hi:[0,1]
	v_pk_mul_f32 v[16:17], v[90:91], v[16:17]
	v_lshlrev_b32_e32 v8, 16, v9
	v_pk_fma_f32 v[24:25], v[82:83], v[16:17], v[24:25] neg_lo:[0,0,1] neg_hi:[0,0,1]
	v_pk_mul_f32 v[16:17], v[86:87], v[16:17]
	v_and_b32_e32 v9, 0xffff0000, v9
	v_pk_fma_f32 v[16:17], v[82:83], v[22:23], v[16:17]
	v_lshlrev_b32_e32 v22, 16, v49
	v_and_b32_e32 v23, 0xffff0000, v49
	v_pk_mul_f32 v[22:23], v[0:1], v[22:23] op_sel_hi:[0,1]
	v_pk_mul_f32 v[8:9], v[0:1], v[8:9] op_sel_hi:[0,1]
	v_pk_mul_f32 v[22:23], v[96:97], v[22:23]
	v_pk_mul_f32 v[8:9], v[92:93], v[8:9]
	v_pk_mul_f32 v[26:27], v[88:89], v[22:23]
	v_cvt_pk_bf16_f32 v169, v6, v7
	v_pk_fma_f32 v[26:27], v[84:85], v[8:9], v[26:27] neg_lo:[0,0,1] neg_hi:[0,0,1]
	v_pk_mul_f32 v[8:9], v[88:89], v[8:9]
	v_lshlrev_b32_e32 v6, 16, v2
	v_pk_fma_f32 v[8:9], v[84:85], v[22:23], v[8:9]
	v_and_b32_e32 v7, 0xffff0000, v2
	v_cvt_pk_bf16_f32 v171, v8, v9
	v_lshlrev_b32_e32 v8, 16, v10
	v_and_b32_e32 v9, 0xffff0000, v10
	v_pk_mul_f32 v[8:9], v[0:1], v[8:9] op_sel_hi:[0,1]
	v_pk_mul_f32 v[6:7], v[0:1], v[6:7] op_sel_hi:[0,1]
	v_pk_mul_f32 v[8:9], v[78:79], v[8:9]
	v_pk_mul_f32 v[6:7], v[74:75], v[6:7]
	v_pk_mul_f32 v[14:15], v[70:71], v[8:9]
	v_lshlrev_b32_e32 v2, 16, v3
	v_pk_fma_f32 v[14:15], v[66:67], v[6:7], v[14:15] neg_lo:[0,0,1] neg_hi:[0,0,1]
	v_pk_mul_f32 v[6:7], v[70:71], v[6:7]
	v_and_b32_e32 v3, 0xffff0000, v3
	v_pk_fma_f32 v[6:7], v[66:67], v[8:9], v[6:7]
	v_lshlrev_b32_e32 v8, 16, v11
	v_and_b32_e32 v9, 0xffff0000, v11
	v_pk_mul_f32 v[8:9], v[0:1], v[8:9] op_sel_hi:[0,1]
	v_pk_mul_f32 v[2:3], v[0:1], v[2:3] op_sel_hi:[0,1]
	v_pk_mul_f32 v[8:9], v[80:81], v[8:9]
	v_pk_mul_f32 v[2:3], v[76:77], v[2:3]
	v_pk_mul_f32 v[10:11], v[72:73], v[8:9]
	v_cvt_pk_bf16_f32 v170, v16, v17
	v_pk_fma_f32 v[10:11], v[68:69], v[2:3], v[10:11] neg_lo:[0,0,1] neg_hi:[0,0,1]
	v_pk_mul_f32 v[2:3], v[72:73], v[2:3]
	v_lshlrev_b32_e32 v16, 16, v12
	v_and_b32_e32 v17, 0xffff0000, v12
	v_pk_fma_f32 v[2:3], v[68:69], v[8:9], v[2:3]
	v_lshlrev_b32_e32 v8, 16, v4
	v_and_b32_e32 v9, 0xffff0000, v4
	v_pk_mul_f32 v[16:17], v[0:1], v[16:17] op_sel_hi:[0,1]
	v_pk_mul_f32 v[8:9], v[0:1], v[8:9] op_sel_hi:[0,1]
	v_pk_mul_f32 v[16:17], v[62:63], v[16:17]
	v_lshlrev_b32_e32 v12, 16, v13
	v_and_b32_e32 v13, 0xffff0000, v13
	v_pk_mul_f32 v[8:9], v[58:59], v[8:9]
	v_pk_mul_f32 v[18:19], v[54:55], v[16:17]
	v_lshlrev_b32_e32 v4, 16, v5
	v_and_b32_e32 v5, 0xffff0000, v5
	v_pk_mul_f32 v[12:13], v[0:1], v[12:13] op_sel_hi:[0,1]
	v_pk_fma_f32 v[18:19], v[50:51], v[8:9], v[18:19] neg_lo:[0,0,1] neg_hi:[0,0,1]
	v_pk_mul_f32 v[8:9], v[54:55], v[8:9]
	v_pk_mul_f32 v[4:5], v[0:1], v[4:5] op_sel_hi:[0,1]
	v_pk_mul_f32 v[12:13], v[64:65], v[12:13]
	v_pk_fma_f32 v[8:9], v[50:51], v[16:17], v[8:9]
	v_pk_mul_f32 v[4:5], v[60:61], v[4:5]
	v_pk_mul_f32 v[16:17], v[56:57], v[12:13]
	v_cvt_pk_bf16_f32 v177, v2, v3
	v_lshlrev_b32_e32 v2, 1, v205
	v_lshrrev_b32_e32 v3, 1, v208
	v_pk_fma_f32 v[16:17], v[52:53], v[4:5], v[16:17] neg_lo:[0,0,1] neg_hi:[0,0,1]
	v_pk_mul_f32 v[4:5], v[56:57], v[4:5]
	v_and_b32_e32 v0, 19, v208
	v_and_b32_e32 v2, 8, v2
	v_and_b32_e32 v3, 4, v3
	v_pk_fma_f32 v[4:5], v[52:53], v[12:13], v[4:5]
	v_cvt_pk_bf16_f32 v172, v14, v15
	v_or3_b32 v0, v0, v2, v3
	v_mov_b32_e32 v14, v1
	v_mov_b32_e32 v15, v1
	v_cvt_pk_bf16_f32 v165, v20, v21
	v_cvt_pk_bf16_f32 v166, v24, v25
	v_cvt_pk_bf16_f32 v167, v26, v27
	v_cvt_pk_bf16_f32 v173, v10, v11
	v_cvt_pk_bf16_f32 v174, v18, v19
	v_cvt_pk_bf16_f32 v175, v16, v17
	v_cvt_pk_bf16_f32 v176, v6, v7
	v_cvt_pk_bf16_f32 v178, v8, v9
	v_cvt_pk_bf16_f32 v179, v4, v5
	v_mul_u32_u24_e32 v180, 0x190, v0
	v_mov_b32_e32 v0, v1
	v_mov_b32_e32 v2, v1
	v_mov_b32_e32 v3, v1
	v_mov_b32_e32 v4, v1
	v_mov_b32_e32 v5, v1
	v_mov_b32_e32 v6, v1
	v_mov_b32_e32 v7, v1
	v_mov_b32_e32 v8, v1
	v_mov_b32_e32 v9, v1
	v_mov_b32_e32 v10, v1
	v_mov_b32_e32 v11, v1
	v_mov_b32_e32 v12, v1
	v_mov_b32_e32 v13, v1
	v_mov_b64_e32 v[30:31], v[14:15]
	v_mov_b64_e32 v[46:47], v[14:15]
	v_mov_b64_e32 v[62:63], v[14:15]
	v_mov_b64_e32 v[78:79], v[14:15]
	v_mov_b64_e32 v[28:29], v[12:13]
	v_mov_b64_e32 v[26:27], v[10:11]
	v_mov_b64_e32 v[24:25], v[8:9]
	v_mov_b64_e32 v[22:23], v[6:7]
	v_mov_b64_e32 v[20:21], v[4:5]
	v_mov_b64_e32 v[18:19], v[2:3]
	v_mov_b64_e32 v[16:17], v[0:1]
	v_mov_b64_e32 v[44:45], v[12:13]
	v_mov_b64_e32 v[42:43], v[10:11]
	v_mov_b64_e32 v[40:41], v[8:9]
	v_mov_b64_e32 v[38:39], v[6:7]
	v_mov_b64_e32 v[36:37], v[4:5]
	v_mov_b64_e32 v[34:35], v[2:3]
	v_mov_b64_e32 v[32:33], v[0:1]
	v_mov_b64_e32 v[60:61], v[12:13]
	v_mov_b64_e32 v[58:59], v[10:11]
	v_mov_b64_e32 v[56:57], v[8:9]
	v_mov_b64_e32 v[54:55], v[6:7]
	v_mov_b64_e32 v[52:53], v[4:5]
	v_mov_b64_e32 v[50:51], v[2:3]
	v_mov_b64_e32 v[48:49], v[0:1]
	v_mov_b64_e32 v[76:77], v[12:13]
	v_mov_b64_e32 v[74:75], v[10:11]
	v_mov_b64_e32 v[72:73], v[8:9]
	v_mov_b64_e32 v[70:71], v[6:7]
	v_mov_b64_e32 v[68:69], v[4:5]
	v_mov_b64_e32 v[66:67], v[2:3]
	v_mov_b64_e32 v[64:65], v[0:1]
	s_mov_b32 s100, 0
	s_mov_b32 s101, 0xac00
.LBB0_709:
	s_add_i32 s9, s10, 1
	s_cmp_gt_i32 s10, s1
	s_cbranch_scc1 .Lattn2_stage_only
	v_add3_u32 v0, s100, v180, v206
	ds_read_b128 v[2:5], v0
	ds_read_b128 v[6:9], v0 offset:32
	ds_read_b128 v[10:13], v0 offset:64
	ds_read_b128 v[184:187], v0 offset:96
	ds_read_b128 v[188:191], v0 offset:128
	ds_read_b128 v[192:195], v0 offset:160
	ds_read_b128 v[196:199], v0 offset:192
	s_mov_b32 s11, s101
	v_add_u32_e32 v247, s11, v227
	v_add_u32_e32 v248, s11, v228
	v_add_u32_e32 v249, s11, v229
	v_add_u32_e32 v250, s11, v200
	v_add_u32_e32 v251, s11, v202
	s_cmp_lt_u32 s10, s7
	s_cselect_b64 s[16:17], -1, 0
	s_cmp_lg_u64 s[16:17], 0
	s_addc_u32 s6, s6, 0
	s_mov_b32 s22, s14
	s_mov_b32 s23, s15
	s_mov_b32 s26, s14
	s_mov_b32 s27, s15
	v_mov_b32_e32 v80, v213
	v_mov_b32_e32 v81, v80
	v_mov_b32_e32 v82, v80
	v_mov_b32_e32 v83, v80
	v_mov_b32_e32 v84, v80
	v_mov_b32_e32 v85, v80
	v_mov_b32_e32 v86, v80
	v_mov_b32_e32 v87, v80
	v_mov_b32_e32 v88, v80
	v_mov_b32_e32 v89, v80
	v_mov_b32_e32 v90, v80
	v_mov_b32_e32 v91, v80
	v_mov_b32_e32 v92, v80
	v_mov_b32_e32 v93, v80
	v_mov_b32_e32 v94, v80
	v_mov_b32_e32 v95, v80
	s_mov_b32 s10, s100
	s_waitcnt lgkmcnt(6)
	v_mfma_f32_32x32x16_bf16 v[96:111], v[2:5], v[132:135], v[80:95]
	s_mul_i32 s11, s6, 0x6000
	s_waitcnt vmcnt(4)
	ds_write_b128 v247, v[112:115]
	buffer_load_dwordx4 v[112:115], v207, s[20:23], s11 offen
	ds_read_b128 v[2:5], v0 offset:224
	s_waitcnt lgkmcnt(6)
	v_mfma_f32_32x32x16_bf16 v[96:111], v[6:9], v[136:139], v[96:111]
	ds_read_b128 v[6:9], v0 offset:256
	s_waitcnt lgkmcnt(6)
	v_mfma_f32_32x32x16_bf16 v[96:111], v[10:13], v[140:143], v[96:111]
	s_add_i32 s16, s11, 0x2000
	s_waitcnt vmcnt(4)
	ds_write_b128 v248, v[116:119]
	buffer_load_dwordx4 v[116:119], v207, s[20:23], s16 offen
	ds_read_b128 v[10:13], v0 offset:288
	s_waitcnt lgkmcnt(6)
	v_mfma_f32_32x32x16_bf16 v[96:111], v[184:187], v[144:147], v[96:111]
	ds_read_b128 v[184:187], v0 offset:320
	s_waitcnt lgkmcnt(6)
	v_mfma_f32_32x32x16_bf16 v[96:111], v[188:191], v[148:151], v[96:111]
	s_addk_i32 s11, 0x4000
	s_waitcnt vmcnt(4)
	ds_write_b128 v249, v[120:123]
	buffer_load_dwordx4 v[120:123], v207, s[20:23], s11 offen
	ds_read_b128 v[188:191], v0 offset:352
	s_waitcnt lgkmcnt(6)
	v_mfma_f32_32x32x16_bf16 v[96:111], v[192:195], v[152:155], v[96:111]
	ds_read_b128 v[192:195], v0 offset:12800
	s_waitcnt lgkmcnt(6)
	v_mfma_f32_32x32x16_bf16 v[96:111], v[196:199], v[156:159], v[96:111]
	s_lshl_b32 s11, s6, 7
	s_waitcnt vmcnt(4)
	ds_write_b128 v250, v[124:127] offset:25600
	buffer_load_dwordx4 v[124:127], v209, s[24:27], s11 offen
	ds_read_b128 v[196:199], v0 offset:12832
	s_waitcnt lgkmcnt(6)
	v_mfma_f32_32x32x16_bf16 v[96:111], v[2:5], v[160:163], v[96:111]
	ds_read_b128 v[2:5], v0 offset:12864
	s_waitcnt lgkmcnt(6)
	v_mfma_f32_32x32x16_bf16 v[96:111], v[6:9], v[164:167], v[96:111]
	s_add_i32 s11, s11, 0x100000
	s_waitcnt vmcnt(4)
	ds_write_b128 v251, v[128:131] offset:25600
	buffer_load_dwordx4 v[128:131], v209, s[24:27], s11 offen
	ds_read_b128 v[6:9], v0 offset:12896
	s_waitcnt lgkmcnt(6)
	v_mfma_f32_32x32x16_bf16 v[96:111], v[10:13], v[172:175], v[96:111]
	ds_read_b128 v[10:13], v0 offset:12928
	s_waitcnt lgkmcnt(6)
	v_mfma_f32_32x32x16_bf16 v[96:111], v[184:187], v[168:171], v[96:111]
	ds_read_b128 v[184:187], v0 offset:12960
	s_waitcnt lgkmcnt(6)
	v_mfma_f32_32x32x16_bf16 v[96:111], v[188:191], v[176:179], v[96:111]
	ds_read_b128 v[188:191], v0 offset:12992
	s_waitcnt lgkmcnt(6)
	v_mfma_f32_32x32x16_bf16 v[80:95], v[192:195], v[132:135], v[80:95]
	s_nop 8
	v_exp_f32_e32 v203, v96
	v_exp_f32_e32 v208, v97
	ds_read_b128 v[192:195], v0 offset:13024
	s_waitcnt lgkmcnt(6)
	v_mfma_f32_32x32x16_bf16 v[80:95], v[196:199], v[136:139], v[80:95]
	v_add_f32_e32 v14, v208, v203
	v_add_f32_e32 v96, v182, v14
	ds_read_b128 v[196:199], v0 offset:13056
	s_waitcnt lgkmcnt(6)
	v_mfma_f32_32x32x16_bf16 v[80:95], v[2:5], v[140:143], v[80:95]
	v_exp_f32_e32 v15, v98
	v_exp_f32_e32 v183, v99
	v_exp_f32_e32 v14, v100
	v_exp_f32_e32 v182, v101
	ds_read_b128 v[2:5], v0 offset:13088
	s_waitcnt lgkmcnt(6)
	v_mfma_f32_32x32x16_bf16 v[80:95], v[6:9], v[144:147], v[80:95]
	v_add_f32_e64 v6, v182, v14
	v_add_f32_e64 v7, v183, v15
	v_add_f32_e32 v7, v7, v96
	v_add_f32_e32 v98, v6, v7
	ds_read_b128 v[6:9], v0 offset:13120
	s_waitcnt lgkmcnt(6)
	v_mfma_f32_32x32x16_bf16 v[80:95], v[10:13], v[148:151], v[80:95]
	v_exp_f32_e32 v231, v102
	v_exp_f32_e32 v233, v103
	v_exp_f32_e32 v230, v104
	v_exp_f32_e32 v232, v105
	ds_read_b128 v[10:13], v0 offset:13152
	s_waitcnt lgkmcnt(6)
	v_mfma_f32_32x32x16_bf16 v[80:95], v[184:187], v[152:155], v[80:95]
	v_add_f32_e64 v96, v232, v230
	v_add_f32_e64 v97, v233, v231
	v_add_f32_e32 v0, v97, v98
	v_add_f32_e32 v0, v96, v0
	v_add3_u32 v234, s10, v181, v206
	ds_read_b128 v[96:99], v234 offset:25600
	s_waitcnt lgkmcnt(6)
	v_mfma_f32_32x32x16_bf16 v[80:95], v[188:191], v[156:159], v[80:95]
	v_exp_f32_e32 v187, v106
	v_exp_f32_e32 v189, v107
	v_exp_f32_e32 v186, v108
	v_exp_f32_e32 v188, v109
	ds_read_b128 v[100:103], v234 offset:30208
	s_waitcnt lgkmcnt(6)
	v_mfma_f32_32x32x16_bf16 v[80:95], v[192:195], v[160:163], v[80:95]
	v_add_f32_e64 v104, v188, v186
	v_add_f32_e64 v105, v189, v187
	v_add_f32_e32 v0, v105, v0
	v_add_f32_e32 v190, v104, v0
	ds_read_b128 v[104:107], v234 offset:34816
	s_waitcnt lgkmcnt(6)
	v_mfma_f32_32x32x16_bf16 v[80:95], v[196:199], v[164:167], v[80:95]
	s_barrier
	v_exp_f32_e32 v192, v110
	v_exp_f32_e32 v194, v111
	ds_read_b128 v[108:111], v234 offset:39424
	s_waitcnt lgkmcnt(6)
	v_mfma_f32_32x32x16_bf16 v[80:95], v[2:5], v[172:175], v[80:95]
	v_cvt_pk_bf16_f32 v2, v203, v208
	v_cvt_pk_bf16_f32 v3, v15, v183
	v_cvt_pk_bf16_f32 v4, v14, v182
	v_cvt_pk_bf16_f32 v5, v231, v233
	ds_read_b128 v[182:185], v234 offset:25632
	s_waitcnt lgkmcnt(6)
	v_mfma_f32_32x32x16_bf16 v[80:95], v[6:9], v[168:171], v[80:95]
	v_cvt_pk_bf16_f32 v6, v230, v232
	v_cvt_pk_bf16_f32 v7, v187, v189
	v_cvt_pk_bf16_f32 v8, v186, v188
	ds_read_b128 v[186:189], v234 offset:30240
	s_waitcnt lgkmcnt(6)
	v_mfma_f32_32x32x16_bf16 v[80:95], v[10:13], v[176:179], v[80:95]
	s_waitcnt lgkmcnt(5)
	v_mfma_f32_32x32x16_bf16 v[64:79], v[96:99], v[2:5], v[64:79]
	ds_read_b128 v[10:13], v234 offset:34848
	s_waitcnt lgkmcnt(5)
	v_mfma_f32_32x32x16_bf16 v[48:63], v[100:103], v[2:5], v[48:63]
	s_nop 6
	v_exp_f32_e32 v195, v80
	v_exp_f32_e32 v193, v81
	ds_read_b128 v[96:99], v234 offset:39456
	v_exp_f32_e32 v191, v82
	v_cvt_pk_bf16_f32 v9, v192, v194
	v_pk_add_f32 v[14:15], v[194:195], v[192:193]
	s_nop 0
	v_pk_add_f32 v[14:15], v[190:191], v[14:15]
	s_waitcnt lgkmcnt(5)
	v_mfma_f32_32x32x16_bf16 v[32:47], v[104:107], v[2:5], v[32:47]
	ds_read_b128 v[100:103], v234 offset:25664
	v_exp_f32_e32 v0, v83
	v_exp_f32_e32 v190, v84
	v_exp_f32_e32 v105, v85
	v_add_f32_e32 v107, v0, v190
	s_waitcnt lgkmcnt(5)
	v_mfma_f32_32x32x16_bf16 v[16:31], v[108:111], v[2:5], v[16:31]
	ds_read_b128 v[80:83], v234 offset:30272
	v_exp_f32_e32 v106, v86
	v_exp_f32_e32 v104, v87
	s_nop 0
	v_pk_add_f32 v[108:109], v[104:105], v[106:107]
	s_waitcnt lgkmcnt(5)
	v_mfma_f32_32x32x16_bf16 v[64:79], v[182:185], v[6:9], v[64:79]
	ds_read_b128 v[2:5], v234 offset:34880
	v_exp_f32_e32 v111, v88
	v_exp_f32_e32 v185, v89
	s_waitcnt lgkmcnt(5)
	v_mfma_f32_32x32x16_bf16 v[48:63], v[186:189], v[6:9], v[48:63]
	v_exp_f32_e32 v110, v90
	v_exp_f32_e32 v184, v91
	ds_read_b128 v[84:87], v234 offset:39488
	v_pk_add_f32 v[182:183], v[184:185], v[110:111]
	s_waitcnt lgkmcnt(5)
	v_mfma_f32_32x32x16_bf16 v[32:47], v[10:13], v[6:9], v[32:47]
	ds_read_b128 v[88:91], v234 offset:25696
	v_exp_f32_e32 v187, v92
	v_exp_f32_e32 v189, v93
	s_waitcnt lgkmcnt(5)
	v_mfma_f32_32x32x16_bf16 v[16:31], v[96:99], v[6:9], v[16:31]
	v_exp_f32_e32 v186, v94
	v_exp_f32_e32 v188, v95
	v_add_f32_e32 v92, v14, v15
	v_add_f32_e32 v92, v109, v92
	v_add_f32_e32 v6, v108, v92
	ds_read_b128 v[10:13], v234 offset:30304
	v_add_f32_e32 v6, v183, v6
	v_pk_add_f32 v[14:15], v[188:189], v[186:187]
	v_add_f32_e32 v6, v182, v6
	v_add_f32_e32 v6, v15, v6
	v_add_f32_e32 v182, v14, v6
	v_cvt_pk_bf16_f32 v6, v195, v193
	v_cvt_pk_bf16_f32 v7, v191, v0
	v_cvt_pk_bf16_f32 v8, v190, v105
	v_cvt_pk_bf16_f32 v9, v106, v104
	v_cvt_pk_bf16_f32 v92, v111, v185
	v_cvt_pk_bf16_f32 v93, v110, v184
	v_cvt_pk_bf16_f32 v94, v187, v189
	v_cvt_pk_bf16_f32 v95, v186, v188
	s_waitcnt lgkmcnt(5)
	v_mfma_f32_32x32x16_bf16 v[64:79], v[100:103], v[6:9], v[64:79]
	ds_read_b128 v[96:99], v234 offset:34912
	s_waitcnt lgkmcnt(5)
	v_mfma_f32_32x32x16_bf16 v[48:63], v[80:83], v[6:9], v[48:63]
	ds_read_b128 v[100:103], v234 offset:39520
	s_waitcnt lgkmcnt(5)
	v_mfma_f32_32x32x16_bf16 v[32:47], v[2:5], v[6:9], v[32:47]
	s_waitcnt lgkmcnt(4)
	v_mfma_f32_32x32x16_bf16 v[16:31], v[84:87], v[6:9], v[16:31]
	s_waitcnt lgkmcnt(3)
	v_mfma_f32_32x32x16_bf16 v[64:79], v[88:91], v[92:95], v[64:79]
	s_waitcnt lgkmcnt(2)
	v_mfma_f32_32x32x16_bf16 v[48:63], v[10:13], v[92:95], v[48:63]
	s_waitcnt lgkmcnt(1)
	v_mfma_f32_32x32x16_bf16 v[32:47], v[96:99], v[92:95], v[32:47]
	s_waitcnt lgkmcnt(0)
	v_mfma_f32_32x32x16_bf16 v[16:31], v[100:103], v[92:95], v[16:31]
.LBB0_711:
	s_mov_b32 s100, s101
	s_add_i32 s101, s101, 0xac00
	s_cmp_eq_u32 s101, 0x20400
	s_cselect_b32 s101, 0, s101
	s_cmp_eq_u32 s8, s9
	s_waitcnt lgkmcnt(0)
	s_cbranch_scc1 .Lattn2_exit
	s_mov_b32 s10, s9
	s_branch .LBB0_709
.Lattn2_stage_only:
	s_mov_b32 s11, s101
	v_add_u32_e32 v247, s11, v227
	v_add_u32_e32 v248, s11, v228
	v_add_u32_e32 v249, s11, v229
	v_add_u32_e32 v250, s11, v200
	v_add_u32_e32 v251, s11, v202
	s_cmp_lt_u32 s10, s7
	s_cselect_b64 s[16:17], -1, 0
	s_cmp_lg_u64 s[16:17], 0
	s_addc_u32 s6, s6, 0
	s_mov_b32 s22, s14
	s_mov_b32 s23, s15
	s_mov_b32 s26, s14
	s_mov_b32 s27, s15
	s_mul_i32 s11, s6, 0x6000
	s_waitcnt vmcnt(4)
	ds_write_b128 v247, v[112:115]
	buffer_load_dwordx4 v[112:115], v207, s[20:23], s11 offen
	s_add_i32 s16, s11, 0x2000
	s_waitcnt vmcnt(4)
	ds_write_b128 v248, v[116:119]
	buffer_load_dwordx4 v[116:119], v207, s[20:23], s16 offen
	s_addk_i32 s11, 0x4000
	s_waitcnt vmcnt(4)
	ds_write_b128 v249, v[120:123]
	buffer_load_dwordx4 v[120:123], v207, s[20:23], s11 offen
	s_lshl_b32 s11, s6, 7
	s_waitcnt vmcnt(4)
	ds_write_b128 v250, v[124:127] offset:25600
	buffer_load_dwordx4 v[124:127], v209, s[24:27], s11 offen
	s_add_i32 s11, s11, 0x100000
	s_waitcnt vmcnt(4)
	ds_write_b128 v251, v[128:131] offset:25600
	buffer_load_dwordx4 v[128:131], v209, s[24:27], s11 offen
	s_waitcnt lgkmcnt(0)
	s_barrier
	s_branch .LBB0_711

	.amdhsa_kernel _Z8fwd_mega6Params
		.amdhsa_group_segment_fixed_size 0
		.amdhsa_private_segment_fixed_size 0
		.amdhsa_kernarg_size 400
		.amdhsa_user_sgpr_count 2
		.amdhsa_user_sgpr_dispatch_ptr 0
		.amdhsa_user_sgpr_queue_ptr 0
		.amdhsa_user_sgpr_kernarg_segment_ptr 1
		.amdhsa_user_sgpr_dispatch_id 0
		.amdhsa_user_sgpr_kernarg_preload_length 0
		.amdhsa_user_sgpr_kernarg_preload_offset 0
		.amdhsa_user_sgpr_private_segment_size 0
		.amdhsa_uses_dynamic_stack 0
		.amdhsa_enable_private_segment 0
		.amdhsa_system_sgpr_workgroup_id_x 1
		.amdhsa_system_sgpr_workgroup_id_y 0
		.amdhsa_system_sgpr_workgroup_id_z 0
		.amdhsa_system_sgpr_workgroup_info 0
		.amdhsa_system_vgpr_workitem_id 2
		.amdhsa_next_free_vgpr 252
		.amdhsa_next_free_sgpr 102
		.amdhsa_accum_offset 252
		.amdhsa_reserve_vcc 1
		.amdhsa_float_round_mode_32 0
		.amdhsa_float_round_mode_16_64 0
		.amdhsa_float_denorm_mode_32 3
		.amdhsa_float_denorm_mode_16_64 3
		.amdhsa_dx10_clamp 1
		.amdhsa_ieee_mode 1
		.amdhsa_fp16_overflow 0
		.amdhsa_tg_split 0
		.amdhsa_exception_fp_ieee_invalid_op 0
		.amdhsa_exception_fp_denorm_src 0
		.amdhsa_exception_fp_ieee_div_zero 0
		.amdhsa_exception_fp_ieee_overflow 0
		.amdhsa_exception_fp_ieee_underflow 0
		.amdhsa_exception_fp_ieee_inexact 0
		.amdhsa_exception_int_div_zero 0
	.end_amdhsa_kernel

amdhsa.kernels:
  - .agpr_count:     0
    .args:
      - .offset:         0
        .size:           144
        .value_kind:     by_value
      - .offset:         144
        .size:           4
        .value_kind:     hidden_block_count_x
      - .offset:         148
        .size:           4
        .value_kind:     hidden_block_count_y
      - .offset:         152
        .size:           4
        .value_kind:     hidden_block_count_z
      - .offset:         156
        .size:           2
        .value_kind:     hidden_group_size_x
      - .offset:         158
        .size:           2
        .value_kind:     hidden_group_size_y
      - .offset:         160
        .size:           2
        .value_kind:     hidden_group_size_z
      - .offset:         162
        .size:           2
        .value_kind:     hidden_remainder_x
      - .offset:         164
        .size:           2
        .value_kind:     hidden_remainder_y
      - .offset:         166
        .size:           2
        .value_kind:     hidden_remainder_z
      - .offset:         184
        .size:           8
        .value_kind:     hidden_global_offset_x
      - .offset:         192
        .size:           8
        .value_kind:     hidden_global_offset_y
      - .offset:         200
        .size:           8
        .value_kind:     hidden_global_offset_z
      - .offset:         208
        .size:           2
        .value_kind:     hidden_grid_dims
      - .offset:         232
        .size:           8
        .value_kind:     hidden_multigrid_sync_arg
      - .offset:         264
        .size:           4
        .value_kind:     hidden_dynamic_lds_size
    .group_segment_fixed_size: 0
    .kernarg_segment_align: 8
    .kernarg_segment_size: 400
    .language:       OpenCL C
    .language_version:
      - 2
      - 0
    .max_flat_workgroup_size: 512
    .name:           _Z8fwd_mega6Params
    .private_segment_fixed_size: 0
    .sgpr_count:     108
    .sgpr_spill_count: 212
    .symbol:         _Z8fwd_mega6Params.kd
    .uniform_work_group_size: 1
    .uses_dynamic_stack: false
    .vgpr_count:     252
    .vgpr_spill_count: 0
    .wavefront_size: 64
